# up-phase epilogue 1: 64 serialized gate loads software-pipelined (24 in flight in free VGPR slots, counted vmcnt)
# speedup vs baseline: 1.0027x; 1.0027x over previous
; DI void gemm8_accum(f32x4 (&acc)[8][4], const bf16_t* a, size_t lda, const bf16_t* b, size_t ldb, int nkb, bf16_t* L,
;                     const bool pre, const bf16_t* an, size_t ldan, const bf16_t* bn, size_t ldbn) {
;     ...
;   __syncthreads();
;   g8_store1(L + 32768, ra, lrow, lch);
;   g8_load1(ra, an, ldan, 0, lrow, lch);
;   __builtin_amdgcn_sched_barrier(0);
;   g8_compute<0, 1>(acc, L, wm, wn, lane);
;   __builtin_amdgcn_sched_barrier(0);
;   g8_store1(L + 32768 + 16384, rb, lrow, lch);
;   g8_load1(rb, bn, ldbn, 0, lrow, lch);
;   __builtin_amdgcn_sched_barrier(0);
;   g8_compute<1, 2>(acc, L, wm, wn, lane);
.Lstg_778_c:
	s_mul_i32 s0, s13, 0x2a30
	s_movk_i32 s25, 0x1518
	s_add_u32 s2, s16, s0
	v_mad_u64_u32 v[180:181], s[0:1], v190, s25, v[170:171]
	s_addc_u32 s3, s17, 0
	v_mov_b32_e32 v181, v1
	v_lshl_add_u64 v[172:173], v[180:181], 1, s[2:3]
	v_add_u32_e32 v174, 0x54600, v180
	v_mov_b32_e32 v175, v1
	v_add_u32_e32 v182, 0xa8c00, v180
	v_mov_b32_e32 v183, v1
	v_add_u32_e32 v180, 0xfd200, v180
	v_lshl_add_u64 v[176:177], v[174:175], 1, s[2:3]
	v_lshl_add_u64 v[182:183], v[182:183], 1, s[2:3]
	v_lshl_add_u64 v[184:185], v[180:181], 1, s[2:3]
	s_barrier
	global_load_dwordx4 v[172:175], v[172:173], off offset:2608
	s_nop 0
	global_load_dwordx4 v[176:179], v[176:177], off offset:2608
	s_nop 0
	global_load_dwordx4 v[180:183], v[182:183], off offset:2608
	s_nop 0
	global_load_dwordx4 v[184:187], v[184:185], off offset:2608
	s_mul_i32 s0, s7, 0x2a3000
	s_lshl_b32 s1, s6, 1
	v_readlane_b32 s6, v252, 1
	v_readlane_b32 s7, v252, 2
	s_add_u32 s6, s6, s1
	s_addc_u32 s7, s7, 0
	s_add_i32 s20, 0, 0x10000
	v_add3_u32 v170, s20, v165, v167
	s_waitcnt vmcnt(11)
	ds_write_b128 v170, v[22:25]
	s_waitcnt vmcnt(9)
	ds_write_b128 v170, v[18:21] offset:8192
	ds_write_b128 v170, v[26:29] offset:16384
	s_waitcnt vmcnt(8)
	ds_write_b128 v170, v[30:33] offset:24576
	v_lshlrev_b32_e32 v170, 1, v169
	v_add_u32_e32 v169, 0, v170
	v_add_u32_e32 v194, v169, v188
	ds_read_b128 v[18:21], v194
	ds_read_b128 v[22:25], v194 offset:2048
	ds_read_b128 v[26:29], v194 offset:4096
	ds_read_b128 v[30:33], v194 offset:6144
	ds_read_b128 v[190:193], v194 offset:8192
	ds_read_b128 v[198:201], v194 offset:10240
	ds_read_b128 v[206:209], v194 offset:12288
	ds_read_b128 v[210:213], v194 offset:14336
	v_add_u32_e32 v169, v169, v171
	ds_read_b128 v[214:217], v169 offset:32768
	ds_read_b128 v[218:221], v169 offset:34816
	ds_read_b128 v[222:225], v169 offset:36864
	ds_read_b128 v[226:229], v169 offset:38912
	s_setprio 1
	s_waitcnt lgkmcnt(3)
	v_mfma_f32_16x16x32_bf16 v[158:161], v[214:217], v[18:21], v[158:161]
	s_waitcnt lgkmcnt(2)
	v_mfma_f32_16x16x32_bf16 v[154:157], v[218:221], v[18:21], v[154:157]
	s_waitcnt lgkmcnt(1)
	v_mfma_f32_16x16x32_bf16 v[150:153], v[222:225], v[18:21], v[150:153]
	s_waitcnt lgkmcnt(0)
	v_mfma_f32_16x16x32_bf16 v[18:21], v[226:229], v[18:21], v[146:149]
	v_mfma_f32_16x16x32_bf16 v[142:145], v[214:217], v[22:25], v[142:145]
	v_mfma_f32_16x16x32_bf16 v[138:141], v[218:221], v[22:25], v[138:141]
	v_mfma_f32_16x16x32_bf16 v[134:137], v[222:225], v[22:25], v[134:137]
	v_mfma_f32_16x16x32_bf16 v[22:25], v[226:229], v[22:25], v[130:133]
	v_mfma_f32_16x16x32_bf16 v[126:129], v[214:217], v[26:29], v[126:129]
	v_mfma_f32_16x16x32_bf16 v[122:125], v[218:221], v[26:29], v[122:125]
	v_mfma_f32_16x16x32_bf16 v[118:121], v[222:225], v[26:29], v[118:121]
	v_mfma_f32_16x16x32_bf16 v[26:29], v[226:229], v[26:29], v[114:117]
	v_mfma_f32_16x16x32_bf16 v[110:113], v[214:217], v[30:33], v[110:113]
	v_mfma_f32_16x16x32_bf16 v[106:109], v[218:221], v[30:33], v[106:109]
	v_mfma_f32_16x16x32_bf16 v[102:105], v[222:225], v[30:33], v[102:105]
	v_mfma_f32_16x16x32_bf16 v[30:33], v[226:229], v[30:33], v[98:101]
	v_mfma_f32_16x16x32_bf16 v[94:97], v[214:217], v[190:193], v[94:97]
	v_mfma_f32_16x16x32_bf16 v[90:93], v[218:221], v[190:193], v[90:93]
	v_mfma_f32_16x16x32_bf16 v[86:89], v[222:225], v[190:193], v[86:89]
	v_mfma_f32_16x16x32_bf16 v[82:85], v[226:229], v[190:193], v[82:85]
	v_mfma_f32_16x16x32_bf16 v[78:81], v[214:217], v[198:201], v[78:81]
	v_mfma_f32_16x16x32_bf16 v[74:77], v[218:221], v[198:201], v[74:77]
	v_mfma_f32_16x16x32_bf16 v[70:73], v[222:225], v[198:201], v[70:73]
	v_mfma_f32_16x16x32_bf16 v[66:69], v[226:229], v[198:201], v[66:69]
	v_mfma_f32_16x16x32_bf16 v[62:65], v[214:217], v[206:209], v[62:65]
	v_mfma_f32_16x16x32_bf16 v[58:61], v[218:221], v[206:209], v[58:61]
	v_mfma_f32_16x16x32_bf16 v[54:57], v[222:225], v[206:209], v[54:57]
	v_mfma_f32_16x16x32_bf16 v[50:53], v[226:229], v[206:209], v[50:53]
	v_mfma_f32_16x16x32_bf16 v[46:49], v[214:217], v[210:213], v[46:49]
	v_mfma_f32_16x16x32_bf16 v[42:45], v[218:221], v[210:213], v[42:45]
	v_mfma_f32_16x16x32_bf16 v[38:41], v[222:225], v[210:213], v[38:41]
	v_mfma_f32_16x16x32_bf16 v[34:37], v[226:229], v[210:213], v[34:37]
	s_setprio 0
	v_readlane_b32 s1, v254, 36
	v_mov_b32_e32 v169, v1
	s_nop 0
	v_add3_u32 v98, s1, v165, v167
	v_mov_b32_e32 v167, v1
	v_mov_b32_e32 v165, v1
	s_waitcnt vmcnt(7)
	ds_write_b128 v98, v[14:17]
	s_waitcnt vmcnt(6)
	ds_write_b128 v98, v[2:5] offset:8192
	s_waitcnt vmcnt(5)
	ds_write_b128 v98, v[6:9] offset:16384
	s_waitcnt vmcnt(4)
	ds_write_b128 v98, v[10:13] offset:24576
	v_lshl_add_u64 v[2:3], v[0:1], 1, s[6:7]
	v_lshl_add_u64 v[6:7], v[168:169], 1, s[6:7]
	v_lshl_add_u64 v[10:11], v[166:167], 1, s[6:7]
	v_lshl_add_u64 v[14:15], v[164:165], 1, s[6:7]
	global_load_dwordx4 v[2:5], v[2:3], off
	s_nop 0
	global_load_dwordx4 v[6:9], v[6:7], off
	s_nop 0
	global_load_dwordx4 v[10:13], v[10:11], off
	s_nop 0
	global_load_dwordx4 v[14:17], v[14:15], off
	v_lshlrev_b32_e32 v0, 1, v189
	v_add_u32_e32 v168, 0, v0
	v_add_u32_e32 v169, v168, v188
	ds_read_b128 v[98:101], v169
	ds_read_b128 v[114:117], v169 offset:2048
	ds_read_b128 v[130:133], v169 offset:4096
	ds_read_b128 v[146:149], v169 offset:6144
	ds_read_b128 v[164:167], v169 offset:8192
	ds_read_b128 v[190:193], v169 offset:10240
	ds_read_b128 v[198:201], v169 offset:12288
	ds_read_b128 v[206:209], v169 offset:14336
	v_add_u32_e32 v168, v168, v171
	ds_read_b128 v[210:213], v168 offset:32768
	ds_read_b128 v[214:217], v168 offset:34816
	ds_read_b128 v[218:221], v168 offset:36864
	ds_read_b128 v[222:225], v168 offset:38912
	s_setprio 1
	s_waitcnt lgkmcnt(3)
; DI void gemm8_accum(f32x4 (&acc)[8][4], const bf16_t* a, size_t lda, const bf16_t* b, size_t ldb, int nkb, bf16_t* L,
;                     const bool pre, const bf16_t* an, size_t ldan, const bf16_t* bn, size_t ldbn) {
;     ...
;   g8_store1(L + 32768 + 16384, rb, lrow, lch);
;   g8_load1(rb, bn, ldbn, 0, lrow, lch);
;   __builtin_amdgcn_sched_barrier(0);
;   g8_compute<1, 2>(acc, L, wm, wn, lane);
;   __syncthreads();
;   g8_store1(L, ra, lrow, lch);
;   __builtin_amdgcn_sched_barrier(0);
;   g8_compute<0, 1>(acc, L + 32768, wm, wn, lane);
;   __builtin_amdgcn_sched_barrier(0);
;   g8_store1(L + 16384, rb, lrow, lch);
;   __builtin_amdgcn_sched_barrier(0);
;   g8_compute<1, 2>(acc, L + 32768, wm, wn, lane);
	v_mfma_f32_16x16x32_bf16 v[158:161], v[210:213], v[98:101], v[158:161]
	s_waitcnt lgkmcnt(2)
	v_mfma_f32_16x16x32_bf16 v[154:157], v[214:217], v[98:101], v[154:157]
	s_waitcnt lgkmcnt(1)
	v_mfma_f32_16x16x32_bf16 v[150:153], v[218:221], v[98:101], v[150:153]
	s_waitcnt lgkmcnt(0)
	v_mfma_f32_16x16x32_bf16 v[18:21], v[222:225], v[98:101], v[18:21]
	v_mfma_f32_16x16x32_bf16 v[98:101], v[210:213], v[114:117], v[142:145]
	v_mfma_f32_16x16x32_bf16 v[138:141], v[214:217], v[114:117], v[138:141]
	v_mfma_f32_16x16x32_bf16 v[134:137], v[218:221], v[114:117], v[134:137]
	v_mfma_f32_16x16x32_bf16 v[22:25], v[222:225], v[114:117], v[22:25]
	v_mfma_f32_16x16x32_bf16 v[114:117], v[210:213], v[130:133], v[126:129]
	v_mfma_f32_16x16x32_bf16 v[122:125], v[214:217], v[130:133], v[122:125]
	v_mfma_f32_16x16x32_bf16 v[118:121], v[218:221], v[130:133], v[118:121]
	v_mfma_f32_16x16x32_bf16 v[26:29], v[222:225], v[130:133], v[26:29]
	v_mfma_f32_16x16x32_bf16 v[110:113], v[210:213], v[146:149], v[110:113]
	v_mfma_f32_16x16x32_bf16 v[106:109], v[214:217], v[146:149], v[106:109]
	v_mfma_f32_16x16x32_bf16 v[102:105], v[218:221], v[146:149], v[102:105]
	v_mfma_f32_16x16x32_bf16 v[30:33], v[222:225], v[146:149], v[30:33]
	v_mfma_f32_16x16x32_bf16 v[94:97], v[210:213], v[164:167], v[94:97]
	v_mfma_f32_16x16x32_bf16 v[90:93], v[214:217], v[164:167], v[90:93]
	v_mfma_f32_16x16x32_bf16 v[86:89], v[218:221], v[164:167], v[86:89]
	v_mfma_f32_16x16x32_bf16 v[82:85], v[222:225], v[164:167], v[82:85]
	v_mfma_f32_16x16x32_bf16 v[78:81], v[210:213], v[190:193], v[78:81]
	v_mfma_f32_16x16x32_bf16 v[74:77], v[214:217], v[190:193], v[74:77]
	v_mfma_f32_16x16x32_bf16 v[70:73], v[218:221], v[190:193], v[70:73]
	v_mfma_f32_16x16x32_bf16 v[66:69], v[222:225], v[190:193], v[66:69]
	v_mfma_f32_16x16x32_bf16 v[62:65], v[210:213], v[198:201], v[62:65]
	v_mfma_f32_16x16x32_bf16 v[58:61], v[214:217], v[198:201], v[58:61]
	v_mfma_f32_16x16x32_bf16 v[54:57], v[218:221], v[198:201], v[54:57]
	v_mfma_f32_16x16x32_bf16 v[50:53], v[222:225], v[198:201], v[50:53]
	v_mfma_f32_16x16x32_bf16 v[46:49], v[210:213], v[206:209], v[46:49]
	v_mfma_f32_16x16x32_bf16 v[42:45], v[214:217], v[206:209], v[42:45]
	v_mfma_f32_16x16x32_bf16 v[38:41], v[218:221], v[206:209], v[38:41]
	v_mfma_f32_16x16x32_bf16 v[34:37], v[222:225], v[206:209], v[34:37]
	s_setprio 0
	s_barrier
	s_waitcnt vmcnt(7)
	ds_write_b128 v163, v[172:175]
	s_waitcnt vmcnt(6)
	ds_write_b128 v163, v[176:179] offset:8192
	s_waitcnt vmcnt(5)
	ds_write_b128 v163, v[180:183] offset:16384
	s_waitcnt vmcnt(4)
	ds_write_b128 v163, v[184:187] offset:24576
	v_add3_u32 v168, s20, v170, v188
	ds_read_b128 v[126:129], v168
	ds_read_b128 v[130:133], v168 offset:2048
	ds_read_b128 v[142:145], v168 offset:4096
	ds_read_b128 v[146:149], v168 offset:6144
	ds_read_b128 v[164:167], v168 offset:8192
	ds_read_b128 v[172:175], v168 offset:10240
	ds_read_b128 v[176:179], v168 offset:12288
	ds_read_b128 v[180:183], v168 offset:14336
	v_add3_u32 v168, s1, v170, v171
	ds_read_b128 v[184:187], v168
	ds_read_b128 v[190:193], v168 offset:2048
	ds_read_b128 v[198:201], v168 offset:4096
	ds_read_b128 v[206:209], v168 offset:6144
	s_setprio 1
	s_waitcnt lgkmcnt(3)
	v_mfma_f32_16x16x32_bf16 v[158:161], v[184:187], v[126:129], v[158:161]
	s_waitcnt lgkmcnt(2)
	v_mfma_f32_16x16x32_bf16 v[154:157], v[190:193], v[126:129], v[154:157]
	s_waitcnt lgkmcnt(1)
	v_mfma_f32_16x16x32_bf16 v[150:153], v[198:201], v[126:129], v[150:153]
	s_waitcnt lgkmcnt(0)
	v_mfma_f32_16x16x32_bf16 v[18:21], v[206:209], v[126:129], v[18:21]
	v_mfma_f32_16x16x32_bf16 v[98:101], v[184:187], v[130:133], v[98:101]
	v_mfma_f32_16x16x32_bf16 v[126:129], v[190:193], v[130:133], v[138:141]
	v_mfma_f32_16x16x32_bf16 v[134:137], v[198:201], v[130:133], v[134:137]
	v_mfma_f32_16x16x32_bf16 v[130:133], v[206:209], v[130:133], v[22:25]
	v_mfma_f32_16x16x32_bf16 v[114:117], v[184:187], v[142:145], v[114:117]
	v_mfma_f32_16x16x32_bf16 v[122:125], v[190:193], v[142:145], v[122:125]
	v_mfma_f32_16x16x32_bf16 v[118:121], v[198:201], v[142:145], v[118:121]
	v_mfma_f32_16x16x32_bf16 v[26:29], v[206:209], v[142:145], v[26:29]
	v_mfma_f32_16x16x32_bf16 v[110:113], v[184:187], v[146:149], v[110:113]
	v_mfma_f32_16x16x32_bf16 v[106:109], v[190:193], v[146:149], v[106:109]
	v_mfma_f32_16x16x32_bf16 v[102:105], v[198:201], v[146:149], v[102:105]
	v_mfma_f32_16x16x32_bf16 v[138:141], v[206:209], v[146:149], v[30:33]
	v_mfma_f32_16x16x32_bf16 v[142:145], v[184:187], v[164:167], v[94:97]
	v_mfma_f32_16x16x32_bf16 v[90:93], v[190:193], v[164:167], v[90:93]
	v_mfma_f32_16x16x32_bf16 v[146:149], v[198:201], v[164:167], v[86:89]
	v_mfma_f32_16x16x32_bf16 v[82:85], v[206:209], v[164:167], v[82:85]
	v_mfma_f32_16x16x32_bf16 v[164:167], v[184:187], v[172:175], v[78:81]
	v_mfma_f32_16x16x32_bf16 v[74:77], v[190:193], v[172:175], v[74:77]
	v_mfma_f32_16x16x32_bf16 v[210:213], v[198:201], v[172:175], v[70:73]
	v_mfma_f32_16x16x32_bf16 v[66:69], v[206:209], v[172:175], v[66:69]
	v_mfma_f32_16x16x32_bf16 v[172:175], v[184:187], v[176:179], v[62:65]
	v_mfma_f32_16x16x32_bf16 v[58:61], v[190:193], v[176:179], v[58:61]
	v_mfma_f32_16x16x32_bf16 v[214:217], v[198:201], v[176:179], v[54:57]
	v_mfma_f32_16x16x32_bf16 v[50:53], v[206:209], v[176:179], v[50:53]
	v_mfma_f32_16x16x32_bf16 v[176:179], v[184:187], v[180:183], v[46:49]
	v_mfma_f32_16x16x32_bf16 v[184:187], v[190:193], v[180:183], v[42:45]
	v_mfma_f32_16x16x32_bf16 v[190:193], v[198:201], v[180:183], v[38:41]
	v_mfma_f32_16x16x32_bf16 v[180:183], v[206:209], v[180:183], v[34:37]
	s_setprio 0
	s_waitcnt vmcnt(3)
	ds_write_b128 v163, v[2:5] offset:32768
	s_waitcnt vmcnt(2)
; DI float bflo(unsigned u) { return __uint_as_float(u << 16); }
; DI float bfhi(unsigned u) { return __uint_as_float(u & 0xffff0000u); }
; DI float sigmoidf(float x) { return __builtin_amdgcn_rcpf(1.f + __expf(-x)); }
; DI float inv_sigmoidf(float x) { return 1.f + __expf(-x); }
; DI void gemm8_accum(f32x4 (&acc)[8][4], const bf16_t* a, size_t lda, const bf16_t* b, size_t ldb, int nkb, bf16_t* L,
;                     const bool pre, const bf16_t* an, size_t ldan, const bf16_t* bn, size_t ldbn) {
;     ...
;   __syncthreads();
;   g8_store1(L, ra, lrow, lch);
;   __builtin_amdgcn_sched_barrier(0);
;   g8_compute<0, 1>(acc, L + 32768, wm, wn, lane);
;   __builtin_amdgcn_sched_barrier(0);
;   g8_store1(L + 16384, rb, lrow, lch);
;   __builtin_amdgcn_sched_barrier(0);
;   g8_compute<1, 2>(acc, L + 32768, wm, wn, lane);
;   __syncthreads();
; __global__ void __launch_bounds__(512, 2) mega(Params p) {
;     ...
;       gemm8_epi(acc8, m0, n0, [&](int m, int n, f32x4& a) {
;         uint2 ua = *(const uint2*)(z + (size_t)m * ZS + C_MA + n);
;         uint2 ub = *(const uint2*)(z + (size_t)m * ZS + C_MB + n);
;         a[0] *= sigmoidf(bflo(ua.x)) * inv_sigmoidf(bflo(ub.x));
;         a[1] *= sigmoidf(bfhi(ua.x)) * inv_sigmoidf(bfhi(ub.x));
;         a[2] *= sigmoidf(bflo(ua.y)) * inv_sigmoidf(bflo(ub.y));
;         a[3] *= sigmoidf(bfhi(ua.y)) * inv_sigmoidf(bfhi(ub.y));
;       });
	ds_write_b128 v163, v[6:9] offset:40960
	s_waitcnt vmcnt(1)
	ds_write_b128 v163, v[10:13] offset:49152
	s_waitcnt vmcnt(0)
	ds_write_b128 v163, v[14:17] offset:57344
	v_add3_u32 v6, s20, v0, v188
	ds_read_b128 v[2:5], v6
	ds_read_b128 v[34:37], v6 offset:2048
	ds_read_b128 v[42:45], v6 offset:4096
	ds_read_b128 v[198:201], v6 offset:6144
	ds_read_b128 v[206:209], v6 offset:8192
	ds_read_b128 v[218:221], v6 offset:10240
	ds_read_b128 v[222:225], v6 offset:12288
	ds_read_b128 v[226:229], v6 offset:14336
	v_add3_u32 v0, s1, v0, v171
	ds_read_b128 v[168:171], v0
	ds_read_b128 v[230:233], v0 offset:2048
	ds_read_b128 v[234:237], v0 offset:4096
	ds_read_b128 v[238:241], v0 offset:6144
	s_setprio 1
	s_waitcnt lgkmcnt(3)
	v_mfma_f32_16x16x32_bf16 v[158:161], v[168:171], v[2:5], v[158:161]
	s_waitcnt lgkmcnt(2)
	v_mfma_f32_16x16x32_bf16 v[6:9], v[230:233], v[2:5], v[154:157]
	s_waitcnt lgkmcnt(1)
	v_mfma_f32_16x16x32_bf16 v[10:13], v[234:237], v[2:5], v[150:153]
	s_waitcnt lgkmcnt(0)
	v_mfma_f32_16x16x32_bf16 v[14:17], v[238:241], v[2:5], v[18:21]
	v_mfma_f32_16x16x32_bf16 v[22:25], v[168:171], v[34:37], v[98:101]
	v_mfma_f32_16x16x32_bf16 v[30:33], v[230:233], v[34:37], v[126:129]
	v_mfma_f32_16x16x32_bf16 v[38:41], v[234:237], v[34:37], v[134:137]
	v_mfma_f32_16x16x32_bf16 v[46:49], v[238:241], v[34:37], v[130:133]
	v_mfma_f32_16x16x32_bf16 v[54:57], v[168:171], v[42:45], v[114:117]
	v_mfma_f32_16x16x32_bf16 v[62:65], v[230:233], v[42:45], v[122:125]
	v_mfma_f32_16x16x32_bf16 v[70:73], v[234:237], v[42:45], v[118:121]
	v_mfma_f32_16x16x32_bf16 v[78:81], v[238:241], v[42:45], v[26:29]
	v_mfma_f32_16x16x32_bf16 v[86:89], v[168:171], v[198:201], v[110:113]
	v_mfma_f32_16x16x32_bf16 v[94:97], v[230:233], v[198:201], v[106:109]
	v_mfma_f32_16x16x32_bf16 v[102:105], v[234:237], v[198:201], v[102:105]
	v_mfma_f32_16x16x32_bf16 v[110:113], v[238:241], v[198:201], v[138:141]
	v_mfma_f32_16x16x32_bf16 v[118:121], v[168:171], v[206:209], v[142:145]
	v_mfma_f32_16x16x32_bf16 v[126:129], v[230:233], v[206:209], v[90:93]
	v_mfma_f32_16x16x32_bf16 v[122:125], v[234:237], v[206:209], v[146:149]
	v_mfma_f32_16x16x32_bf16 v[114:117], v[238:241], v[206:209], v[82:85]
	v_mfma_f32_16x16x32_bf16 v[106:109], v[168:171], v[218:221], v[164:167]
	v_mfma_f32_16x16x32_bf16 v[98:101], v[230:233], v[218:221], v[74:77]
	v_mfma_f32_16x16x32_bf16 v[90:93], v[234:237], v[218:221], v[210:213]
	v_mfma_f32_16x16x32_bf16 v[82:85], v[238:241], v[218:221], v[66:69]
	v_mfma_f32_16x16x32_bf16 v[74:77], v[168:171], v[222:225], v[172:175]
	v_mfma_f32_16x16x32_bf16 v[66:69], v[230:233], v[222:225], v[58:61]
	v_mfma_f32_16x16x32_bf16 v[58:61], v[234:237], v[222:225], v[214:217]
	v_mfma_f32_16x16x32_bf16 v[50:53], v[238:241], v[222:225], v[50:53]
	v_mfma_f32_16x16x32_bf16 v[42:45], v[168:171], v[226:229], v[176:179]
	v_mfma_f32_16x16x32_bf16 v[34:37], v[230:233], v[226:229], v[184:187]
	v_mfma_f32_16x16x32_bf16 v[26:29], v[234:237], v[226:229], v[190:193]
	v_mfma_f32_16x16x32_bf16 v[18:21], v[238:241], v[226:229], v[180:183]
	s_setprio 0
	v_mov_b32_e32 v0, v196
	s_barrier
	v_mov_b64_e32 v[136:137], s[16:17]
	v_ashrrev_i32_e32 v3, 1, v0
	v_and_b32_e32 v2, 0xc0, v0
	v_and_b32_e32 v3, 0xffffff80, v3
	v_and_or_b32 v4, v0, 15, s13
	v_lshrrev_b32_e32 v0, 2, v0
	v_add_u32_e32 v142, v4, v3
	v_and_b32_e32 v0, 12, v0
	v_or3_b32 v0, v2, v0, s12
	v_mad_i64_i32 v[2:3], s[26:27], v142, s35, v[136:137]
	s_mov_b64 s[30:31], 0x1a30
	s_mov_b64 s[42:43], 0x2230
	v_lshl_add_u64 v[138:139], v[2:3], 0, s[30:31]
	v_lshlrev_b32_e32 v0, 1, v0
	v_lshl_add_u64 v[140:141], v[2:3], 0, s[42:43]
	v_lshl_add_u64 v[4:5], v[138:139], 0, v[0:1]
	v_lshl_add_u64 v[2:3], v[140:141], 0, v[0:1]
	s_mov_b32 s88, 0x2a300
	s_mov_b32 s89, 0
	v_mov_b64_e32 v[246:247], v[4:5]
	global_load_dwordx2 v[198:199], v[246:247], off
	global_load_dwordx2 v[200:201], v[246:247], off offset:2048
	global_load_dwordx2 v[202:203], v[246:247], off offset:32
	global_load_dwordx2 v[204:205], v[246:247], off offset:2080
	global_load_dwordx2 v[206:207], v[246:247], off offset:64
	global_load_dwordx2 v[208:209], v[246:247], off offset:2112
	global_load_dwordx2 v[210:211], v[246:247], off offset:96
	global_load_dwordx2 v[212:213], v[246:247], off offset:2144
	v_lshl_add_u64 v[246:247], v[246:247], 0, s[88:89]
	global_load_dwordx2 v[214:215], v[246:247], off
	global_load_dwordx2 v[216:217], v[246:247], off offset:2048
	global_load_dwordx2 v[218:219], v[246:247], off offset:32
	global_load_dwordx2 v[220:221], v[246:247], off offset:2080
	global_load_dwordx2 v[222:223], v[246:247], off offset:64
	global_load_dwordx2 v[224:225], v[246:247], off offset:2112
	global_load_dwordx2 v[226:227], v[246:247], off offset:96
	global_load_dwordx2 v[228:229], v[246:247], off offset:2144
	v_lshl_add_u64 v[246:247], v[246:247], 0, s[88:89]
	global_load_dwordx2 v[230:231], v[246:247], off
	global_load_dwordx2 v[232:233], v[246:247], off offset:2048
	global_load_dwordx2 v[234:235], v[246:247], off offset:32
	global_load_dwordx2 v[236:237], v[246:247], off offset:2080
	global_load_dwordx2 v[238:239], v[246:247], off offset:64
	global_load_dwordx2 v[240:241], v[246:247], off offset:2112
	global_load_dwordx2 v[242:243], v[246:247], off offset:96
	global_load_dwordx2 v[244:245], v[246:247], off offset:2144
	s_waitcnt vmcnt(23)
	v_mov_b64_e32 v[4:5], v[198:199]
	v_lshl_add_u64 v[246:247], v[246:247], 0, s[88:89]
	global_load_dwordx2 v[198:199], v[246:247], off
	v_or_b32_e32 v134, 32, v0
	s_waitcnt vmcnt(23)
; DI float bflo(unsigned u) { return __uint_as_float(u << 16); }
; DI float bfhi(unsigned u) { return __uint_as_float(u & 0xffff0000u); }
; DI float sigmoidf(float x) { return __builtin_amdgcn_rcpf(1.f + __expf(-x)); }
; DI float inv_sigmoidf(float x) { return 1.f + __expf(-x); }
; DI int TID8() { int t = threadIdx.x; asm volatile("" : "+v"(t)); return t; }
; template <class E>
; DI void gemm8_epi(f32x4 (&acc)[8][4], int m0, int n0, E e) {
;   const int tid = TID8(), lane = tid & 63, w = tid >> 6;
;   const int wm = w >> 2, wn = w & 3;
; #pragma unroll
;   for (int i = 0; i < 8; ++i)
; #pragma unroll
;     for (int j = 0; j < 4; ++j) {
;       const int m = m0 + wm * 128 + i * 16 + (lane & 15);
;       const int n = n0 + wn * 64 + j * 16 + (lane >> 4) * 4;
;       e(m, n, acc[i][j]);
;     }
; }
; __global__ void __launch_bounds__(512, 2) mega(Params p) {
;     ...
;       gemm8_epi(acc8, m0, n0, [&](int m, int n, f32x4& a) {
;         uint2 ua = *(const uint2*)(z + (size_t)m * ZS + C_MA + n);
;         uint2 ub = *(const uint2*)(z + (size_t)m * ZS + C_MB + n);
;         a[0] *= sigmoidf(bflo(ua.x)) * inv_sigmoidf(bflo(ub.x));
;         a[1] *= sigmoidf(bfhi(ua.x)) * inv_sigmoidf(bfhi(ub.x));
;         a[2] *= sigmoidf(bflo(ua.y)) * inv_sigmoidf(bflo(ub.y));
;         a[3] *= sigmoidf(bfhi(ua.y)) * inv_sigmoidf(bfhi(ub.y));
;       });
	v_mov_b64_e32 v[2:3], v[200:201]
	global_load_dwordx2 v[200:201], v[246:247], off offset:2048
	v_mov_b32_e32 v135, v1
	v_mov_b32_e32 v172, v196
	s_movk_i32 s1, 0x3c0
	s_movk_i32 s96, 0x1518
	s_nop 0
	v_lshlrev_b32_e32 v130, 16, v4
	v_and_b32_e32 v4, 0xffff0000, v4
	s_nop 0
	v_lshlrev_b32_e32 v131, 16, v2
	v_and_b32_e32 v2, 0xffff0000, v2
	v_mul_f32_e32 v2, 0xbfb8aa3b, v2
	v_exp_f32_e32 v133, v2
	v_lshlrev_b32_e32 v2, 16, v5
	v_mul_f32_e32 v4, 0xbfb8aa3b, v4
	v_mul_f32_e32 v2, 0xbfb8aa3b, v2
	v_exp_f32_e32 v4, v4
	v_exp_f32_e32 v2, v2
	v_and_b32_e32 v5, 0xffff0000, v5
	v_mul_f32_e32 v130, 0xbfb8aa3b, v130
	v_mul_f32_e32 v5, 0xbfb8aa3b, v5
	v_exp_f32_e32 v130, v130
	v_exp_f32_e32 v5, v5
	v_mul_f32_e32 v131, 0xbfb8aa3b, v131
	v_add_f32_e32 v4, 1.0, v4
	v_add_f32_e32 v2, 1.0, v2
	v_exp_f32_e32 v132, v131
	v_rcp_f32_e32 v131, v4
	v_rcp_f32_e32 v4, v2
	v_lshlrev_b32_e32 v2, 16, v3
	v_and_b32_e32 v3, 0xffff0000, v3
	v_mul_f32_e32 v2, 0xbfb8aa3b, v2
	v_mul_f32_e32 v3, 0xbfb8aa3b, v3
	v_add_f32_e32 v130, 1.0, v130
	v_exp_f32_e32 v2, v2
	v_add_f32_e32 v5, 1.0, v5
	v_exp_f32_e32 v3, v3
	v_rcp_f32_e32 v130, v130
	v_rcp_f32_e32 v5, v5
	v_pk_add_f32 v[132:133], v[132:133], 1.0 op_sel_hi:[1,0]
	v_pk_add_f32 v[2:3], v[2:3], 1.0 op_sel_hi:[1,0]
	v_pk_mul_f32 v[130:131], v[130:131], v[132:133]
	v_pk_mul_f32 v[2:3], v[4:5], v[2:3]
	v_lshl_add_u64 v[132:133], v[140:141], 0, v[134:135]
	v_pk_mul_f32 v[4:5], v[160:161], v[2:3]
	v_pk_mul_f32 v[2:3], v[158:159], v[130:131]
	v_lshl_add_u64 v[130:131], v[138:139], 0, v[134:135]
	s_waitcnt vmcnt(23)
	v_mov_b64_e32 v[130:131], v[202:203]
	global_load_dwordx2 v[202:203], v[246:247], off offset:32
	s_nop 0
	s_waitcnt vmcnt(23)
	v_mov_b64_e32 v[132:133], v[204:205]
	global_load_dwordx2 v[204:205], v[246:247], off offset:2080
	s_nop 0
	v_lshlrev_b32_e32 v143, 16, v130
	v_and_b32_e32 v130, 0xffff0000, v130
	v_mul_f32_e32 v130, 0xbfb8aa3b, v130
	v_exp_f32_e32 v130, v130
	v_mul_f32_e32 v143, 0xbfb8aa3b, v143
	v_exp_f32_e32 v143, v143
	v_add_f32_e32 v130, 1.0, v130
	v_rcp_f32_e32 v145, v130
	s_nop 0
	v_and_b32_e32 v130, 0xffff0000, v132
	v_mul_f32_e32 v130, 0xbfb8aa3b, v130
	v_exp_f32_e32 v147, v130
	v_lshlrev_b32_e32 v130, 16, v131
	v_and_b32_e32 v131, 0xffff0000, v131
	v_mul_f32_e32 v130, 0xbfb8aa3b, v130
	v_mul_f32_e32 v131, 0xbfb8aa3b, v131
	v_exp_f32_e32 v130, v130
	v_exp_f32_e32 v131, v131
	v_add_f32_e32 v143, 1.0, v143
	v_rcp_f32_e32 v144, v143
	v_lshlrev_b32_e32 v143, 16, v132
	v_lshlrev_b32_e32 v132, 16, v133
	v_and_b32_e32 v133, 0xffff0000, v133
	v_mul_f32_e32 v132, 0xbfb8aa3b, v132
	v_mul_f32_e32 v133, 0xbfb8aa3b, v133
	v_add_f32_e32 v130, 1.0, v130
	v_exp_f32_e32 v132, v132
	v_add_f32_e32 v131, 1.0, v131
	v_exp_f32_e32 v133, v133
	v_rcp_f32_e32 v130, v130
	v_rcp_f32_e32 v131, v131
	v_mul_f32_e32 v143, 0xbfb8aa3b, v143
	v_pk_add_f32 v[132:133], v[132:133], 1.0 op_sel_hi:[1,0]
	v_exp_f32_e32 v146, v143
	v_pk_mul_f32 v[130:131], v[130:131], v[132:133]
	v_or_b32_e32 v132, 64, v0
	v_mov_b32_e32 v133, v1
	v_pk_mul_f32 v[8:9], v[8:9], v[130:131]
	v_lshl_add_u64 v[130:131], v[138:139], 0, v[132:133]
	s_waitcnt vmcnt(23)
	v_mov_b64_e32 v[130:131], v[206:207]
	global_load_dwordx2 v[206:207], v[246:247], off offset:64
	v_pk_add_f32 v[146:147], v[146:147], 1.0 op_sel_hi:[1,0]
	s_nop 0
	v_pk_mul_f32 v[144:145], v[144:145], v[146:147]
	s_nop 0
	v_pk_mul_f32 v[6:7], v[6:7], v[144:145]
	v_lshl_add_u64 v[144:145], v[140:141], 0, v[132:133]
	s_waitcnt vmcnt(23)
	v_mov_b64_e32 v[144:145], v[208:209]
	global_load_dwordx2 v[208:209], v[246:247], off offset:2112
	s_nop 0
	v_lshlrev_b32_e32 v143, 16, v130
	v_and_b32_e32 v130, 0xffff0000, v130
	v_mul_f32_e32 v130, 0xbfb8aa3b, v130
	v_exp_f32_e32 v130, v130
	v_mul_f32_e32 v143, 0xbfb8aa3b, v143
	v_exp_f32_e32 v143, v143
	v_add_f32_e32 v130, 1.0, v130
	v_rcp_f32_e32 v147, v130
	s_nop 0
	v_and_b32_e32 v130, 0xffff0000, v144
	v_add_f32_e32 v143, 1.0, v143
	v_mul_f32_e32 v130, 0xbfb8aa3b, v130
	v_rcp_f32_e32 v146, v143
	v_lshlrev_b32_e32 v143, 16, v144
	v_exp_f32_e32 v149, v130
	v_lshlrev_b32_e32 v130, 16, v131
	v_and_b32_e32 v131, 0xffff0000, v131
	v_mul_f32_e32 v143, 0xbfb8aa3b, v143
	v_mul_f32_e32 v130, 0xbfb8aa3b, v130
	v_mul_f32_e32 v131, 0xbfb8aa3b, v131
	v_exp_f32_e32 v148, v143
	v_exp_f32_e32 v130, v130
	v_lshlrev_b32_e32 v143, 16, v145
	v_exp_f32_e32 v131, v131
	v_mul_f32_e32 v143, 0xbfb8aa3b, v143
	v_exp_f32_e32 v144, v143
	v_and_b32_e32 v143, 0xffff0000, v145
	v_mul_f32_e32 v143, 0xbfb8aa3b, v143
	v_add_f32_e32 v130, 1.0, v130
	v_add_f32_e32 v131, 1.0, v131
	v_exp_f32_e32 v145, v143
	v_rcp_f32_e32 v130, v130
	v_rcp_f32_e32 v131, v131
	v_pk_add_f32 v[148:149], v[148:149], 1.0 op_sel_hi:[1,0]
	v_pk_add_f32 v[144:145], v[144:145], 1.0 op_sel_hi:[1,0]
	v_pk_mul_f32 v[146:147], v[146:147], v[148:149]
	v_pk_mul_f32 v[130:131], v[130:131], v[144:145]
	v_pk_mul_f32 v[10:11], v[10:11], v[146:147]
	v_pk_mul_f32 v[12:13], v[12:13], v[130:131]
	v_or_b32_e32 v130, 0x60, v0
	v_mov_b32_e32 v131, v1
	v_lshl_add_u64 v[138:139], v[138:139], 0, v[130:131]
	s_waitcnt vmcnt(23)
	v_mov_b64_e32 v[138:139], v[210:211]
	global_load_dwordx2 v[210:211], v[246:247], off offset:96
	v_lshl_add_u64 v[140:141], v[140:141], 0, v[130:131]
	s_waitcnt vmcnt(23)
; DI float bflo(unsigned u) { return __uint_as_float(u << 16); }
; DI float bfhi(unsigned u) { return __uint_as_float(u & 0xffff0000u); }
; DI float sigmoidf(float x) { return __builtin_amdgcn_rcpf(1.f + __expf(-x)); }
; DI float inv_sigmoidf(float x) { return 1.f + __expf(-x); }
; DI int TID8() { int t = threadIdx.x; asm volatile("" : "+v"(t)); return t; }
; template <class E>
; DI void gemm8_epi(f32x4 (&acc)[8][4], int m0, int n0, E e) {
;   const int tid = TID8(), lane = tid & 63, w = tid >> 6;
;   const int wm = w >> 2, wn = w & 3;
; #pragma unroll
;   for (int i = 0; i < 8; ++i)
; #pragma unroll
;     for (int j = 0; j < 4; ++j) {
;       const int m = m0 + wm * 128 + i * 16 + (lane & 15);
;       const int n = n0 + wn * 64 + j * 16 + (lane >> 4) * 4;
;       e(m, n, acc[i][j]);
;     }
; }
; __global__ void __launch_bounds__(512, 2) mega(Params p) {
;     ...
;       gemm8_epi(acc8, m0, n0, [&](int m, int n, f32x4& a) {
;         uint2 ua = *(const uint2*)(z + (size_t)m * ZS + C_MA + n);
;         uint2 ub = *(const uint2*)(z + (size_t)m * ZS + C_MB + n);
;         a[0] *= sigmoidf(bflo(ua.x)) * inv_sigmoidf(bflo(ub.x));
;         a[1] *= sigmoidf(bfhi(ua.x)) * inv_sigmoidf(bfhi(ub.x));
;         a[2] *= sigmoidf(bflo(ua.y)) * inv_sigmoidf(bflo(ub.y));
;         a[3] *= sigmoidf(bfhi(ua.y)) * inv_sigmoidf(bfhi(ub.y));
;       });
	v_mov_b64_e32 v[140:141], v[212:213]
	global_load_dwordx2 v[212:213], v[246:247], off offset:2144
	s_nop 0
	v_lshlrev_b32_e32 v143, 16, v138
	v_and_b32_e32 v138, 0xffff0000, v138
	v_mul_f32_e32 v138, 0xbfb8aa3b, v138
	v_exp_f32_e32 v138, v138
	v_mul_f32_e32 v143, 0xbfb8aa3b, v143
	v_exp_f32_e32 v143, v143
	v_add_f32_e32 v138, 1.0, v138
	v_rcp_f32_e32 v145, v138
	s_nop 0
	v_and_b32_e32 v138, 0xffff0000, v140
	v_mul_f32_e32 v138, 0xbfb8aa3b, v138
	v_exp_f32_e32 v147, v138
	v_lshlrev_b32_e32 v138, 16, v139
	v_and_b32_e32 v139, 0xffff0000, v139
	v_mul_f32_e32 v138, 0xbfb8aa3b, v138
	v_mul_f32_e32 v139, 0xbfb8aa3b, v139
	v_exp_f32_e32 v138, v138
	v_exp_f32_e32 v139, v139
	v_add_f32_e32 v143, 1.0, v143
	v_rcp_f32_e32 v144, v143
	v_lshlrev_b32_e32 v143, 16, v140
	v_lshlrev_b32_e32 v140, 16, v141
	v_and_b32_e32 v141, 0xffff0000, v141
	v_mul_f32_e32 v140, 0xbfb8aa3b, v140
	v_mul_f32_e32 v141, 0xbfb8aa3b, v141
	v_add_f32_e32 v138, 1.0, v138
	v_exp_f32_e32 v140, v140
	v_add_f32_e32 v139, 1.0, v139
	v_exp_f32_e32 v141, v141
	v_rcp_f32_e32 v138, v138
	v_rcp_f32_e32 v139, v139
	v_mul_f32_e32 v143, 0xbfb8aa3b, v143
	v_exp_f32_e32 v146, v143
	v_pk_add_f32 v[140:141], v[140:141], 1.0 op_sel_hi:[1,0]
	v_pk_add_f32 v[146:147], v[146:147], 1.0 op_sel_hi:[1,0]
	v_pk_mul_f32 v[138:139], v[138:139], v[140:141]
	v_pk_mul_f32 v[144:145], v[144:145], v[146:147]
	v_pk_mul_f32 v[16:17], v[16:17], v[138:139]
	v_or_b32_e32 v138, 16, v142
	v_mad_i64_i32 v[140:141], s[26:27], v138, s35, v[136:137]
	v_lshl_add_u64 v[138:139], v[140:141], 0, s[30:31]
	v_pk_mul_f32 v[14:15], v[14:15], v[144:145]
	v_lshl_add_u64 v[144:145], v[138:139], 0, v[0:1]
	s_waitcnt vmcnt(23)
	v_mov_b64_e32 v[144:145], v[214:215]
	v_lshl_add_u64 v[246:247], v[246:247], 0, s[88:89]
	global_load_dwordx2 v[214:215], v[246:247], off
	v_lshl_add_u64 v[140:141], v[140:141], 0, s[42:43]
	v_lshl_add_u64 v[146:147], v[140:141], 0, v[0:1]
	s_waitcnt vmcnt(23)
	v_mov_b64_e32 v[146:147], v[216:217]
	global_load_dwordx2 v[216:217], v[246:247], off offset:2048
	s_nop 0
	v_lshlrev_b32_e32 v143, 16, v144
	v_mul_f32_e32 v143, 0xbfb8aa3b, v143
	v_exp_f32_e32 v143, v143
	s_nop 0
	v_add_f32_e32 v143, 1.0, v143
	v_rcp_f32_e32 v148, v143
	s_nop 0
	v_lshlrev_b32_e32 v143, 16, v146
	v_mul_f32_e32 v143, 0xbfb8aa3b, v143
	v_exp_f32_e32 v150, v143
	v_and_b32_e32 v143, 0xffff0000, v144
	v_mul_f32_e32 v143, 0xbfb8aa3b, v143
	v_exp_f32_e32 v143, v143
	s_nop 0
	v_add_f32_e32 v143, 1.0, v143
	v_rcp_f32_e32 v149, v143
	v_and_b32_e32 v143, 0xffff0000, v146
	v_mul_f32_e32 v143, 0xbfb8aa3b, v143
	v_exp_f32_e32 v151, v143
	v_lshlrev_b32_e32 v143, 16, v145
	v_mul_f32_e32 v143, 0xbfb8aa3b, v143
	v_exp_f32_e32 v143, v143
	v_pk_add_f32 v[150:151], v[150:151], 1.0 op_sel_hi:[1,0]
	v_add_f32_e32 v143, 1.0, v143
	v_rcp_f32_e32 v144, v143
	v_lshlrev_b32_e32 v143, 16, v147
	v_mul_f32_e32 v143, 0xbfb8aa3b, v143
	v_exp_f32_e32 v146, v143
	v_and_b32_e32 v143, 0xffff0000, v145
	v_mul_f32_e32 v143, 0xbfb8aa3b, v143
	v_exp_f32_e32 v143, v143
	v_pk_mul_f32 v[148:149], v[148:149], v[150:151]
	v_add_f32_e32 v143, 1.0, v143
	v_rcp_f32_e32 v145, v143
	v_and_b32_e32 v143, 0xffff0000, v147
	v_mul_f32_e32 v143, 0xbfb8aa3b, v143
	v_exp_f32_e32 v147, v143
	v_pk_mul_f32 v[22:23], v[22:23], v[148:149]
	v_pk_add_f32 v[146:147], v[146:147], 1.0 op_sel_hi:[1,0]
	s_nop 0
	v_pk_mul_f32 v[144:145], v[144:145], v[146:147]
	v_lshl_add_u64 v[146:147], v[140:141], 0, v[134:135]
	v_pk_mul_f32 v[24:25], v[24:25], v[144:145]
	v_lshl_add_u64 v[144:145], v[138:139], 0, v[134:135]
	s_waitcnt vmcnt(23)
	v_mov_b64_e32 v[144:145], v[218:219]
	global_load_dwordx2 v[218:219], v[246:247], off offset:32
	s_nop 0
	s_waitcnt vmcnt(23)
	v_mov_b64_e32 v[146:147], v[220:221]
	global_load_dwordx2 v[220:221], v[246:247], off offset:2080
	s_nop 0
	v_lshlrev_b32_e32 v143, 16, v144
	v_mul_f32_e32 v143, 0xbfb8aa3b, v143
	v_exp_f32_e32 v143, v143
	s_nop 0
	v_add_f32_e32 v143, 1.0, v143
	v_rcp_f32_e32 v148, v143
	s_nop 0
	v_lshlrev_b32_e32 v143, 16, v146
	v_mul_f32_e32 v143, 0xbfb8aa3b, v143
	v_exp_f32_e32 v150, v143
	v_and_b32_e32 v143, 0xffff0000, v144
	v_mul_f32_e32 v143, 0xbfb8aa3b, v143
	v_exp_f32_e32 v143, v143
	s_nop 0
	v_add_f32_e32 v143, 1.0, v143
	v_rcp_f32_e32 v149, v143
	v_and_b32_e32 v143, 0xffff0000, v146
	v_mul_f32_e32 v143, 0xbfb8aa3b, v143
	v_exp_f32_e32 v151, v143
	v_lshlrev_b32_e32 v143, 16, v145
	v_mul_f32_e32 v143, 0xbfb8aa3b, v143
	v_exp_f32_e32 v143, v143
	v_pk_add_f32 v[150:151], v[150:151], 1.0 op_sel_hi:[1,0]
	v_add_f32_e32 v143, 1.0, v143
	v_rcp_f32_e32 v144, v143
	v_lshlrev_b32_e32 v143, 16, v147
	v_mul_f32_e32 v143, 0xbfb8aa3b, v143
	v_exp_f32_e32 v146, v143
	v_and_b32_e32 v143, 0xffff0000, v145
	v_mul_f32_e32 v143, 0xbfb8aa3b, v143
	v_exp_f32_e32 v143, v143
	v_pk_mul_f32 v[148:149], v[148:149], v[150:151]
	v_add_f32_e32 v143, 1.0, v143
	v_rcp_f32_e32 v145, v143
	v_and_b32_e32 v143, 0xffff0000, v147
	v_mul_f32_e32 v143, 0xbfb8aa3b, v143
	v_exp_f32_e32 v147, v143
	v_pk_mul_f32 v[30:31], v[30:31], v[148:149]
	v_pk_add_f32 v[146:147], v[146:147], 1.0 op_sel_hi:[1,0]
	s_nop 0
	v_pk_mul_f32 v[144:145], v[144:145], v[146:147]
	v_lshl_add_u64 v[146:147], v[140:141], 0, v[132:133]
	v_pk_mul_f32 v[32:33], v[32:33], v[144:145]
	v_lshl_add_u64 v[144:145], v[138:139], 0, v[132:133]
	s_waitcnt vmcnt(23)
	v_mov_b64_e32 v[144:145], v[222:223]
	global_load_dwordx2 v[222:223], v[246:247], off offset:64
	v_lshl_add_u64 v[138:139], v[138:139], 0, v[130:131]
	s_waitcnt vmcnt(23)
	v_mov_b64_e32 v[146:147], v[224:225]
	global_load_dwordx2 v[224:225], v[246:247], off offset:2112
	v_lshl_add_u64 v[140:141], v[140:141], 0, v[130:131]
	s_waitcnt vmcnt(23)
; DI float bflo(unsigned u) { return __uint_as_float(u << 16); }
; DI float bfhi(unsigned u) { return __uint_as_float(u & 0xffff0000u); }
; DI float sigmoidf(float x) { return __builtin_amdgcn_rcpf(1.f + __expf(-x)); }
; DI float inv_sigmoidf(float x) { return 1.f + __expf(-x); }
; DI int TID8() { int t = threadIdx.x; asm volatile("" : "+v"(t)); return t; }
; template <class E>
; DI void gemm8_epi(f32x4 (&acc)[8][4], int m0, int n0, E e) {
;   const int tid = TID8(), lane = tid & 63, w = tid >> 6;
;   const int wm = w >> 2, wn = w & 3;
; #pragma unroll
;   for (int i = 0; i < 8; ++i)
; #pragma unroll
;     for (int j = 0; j < 4; ++j) {
;       const int m = m0 + wm * 128 + i * 16 + (lane & 15);
;       const int n = n0 + wn * 64 + j * 16 + (lane >> 4) * 4;
;       e(m, n, acc[i][j]);
;     }
; }
; __global__ void __launch_bounds__(512, 2) mega(Params p) {
;     ...
;       gemm8_epi(acc8, m0, n0, [&](int m, int n, f32x4& a) {
;         uint2 ua = *(const uint2*)(z + (size_t)m * ZS + C_MA + n);
;         uint2 ub = *(const uint2*)(z + (size_t)m * ZS + C_MB + n);
;         a[0] *= sigmoidf(bflo(ua.x)) * inv_sigmoidf(bflo(ub.x));
;         a[1] *= sigmoidf(bfhi(ua.x)) * inv_sigmoidf(bfhi(ub.x));
;         a[2] *= sigmoidf(bflo(ua.y)) * inv_sigmoidf(bflo(ub.y));
;         a[3] *= sigmoidf(bfhi(ua.y)) * inv_sigmoidf(bfhi(ub.y));
;       });
	v_mov_b64_e32 v[138:139], v[226:227]
	global_load_dwordx2 v[226:227], v[246:247], off offset:96
	s_nop 0
	s_waitcnt vmcnt(23)
	v_mov_b64_e32 v[140:141], v[228:229]
	global_load_dwordx2 v[228:229], v[246:247], off offset:2144
	s_nop 0
	v_lshlrev_b32_e32 v143, 16, v144
	v_mul_f32_e32 v143, 0xbfb8aa3b, v143
	v_exp_f32_e32 v143, v143
	s_nop 0
	v_add_f32_e32 v143, 1.0, v143
	v_rcp_f32_e32 v148, v143
	s_nop 0
	v_lshlrev_b32_e32 v143, 16, v146
	v_mul_f32_e32 v143, 0xbfb8aa3b, v143
	v_exp_f32_e32 v150, v143
	v_and_b32_e32 v143, 0xffff0000, v144
	v_mul_f32_e32 v143, 0xbfb8aa3b, v143
	v_exp_f32_e32 v143, v143
	s_nop 0
	v_add_f32_e32 v143, 1.0, v143
	v_rcp_f32_e32 v149, v143
	v_and_b32_e32 v143, 0xffff0000, v146
	v_mul_f32_e32 v143, 0xbfb8aa3b, v143
	v_exp_f32_e32 v151, v143
	v_lshlrev_b32_e32 v143, 16, v145
	v_mul_f32_e32 v143, 0xbfb8aa3b, v143
	v_exp_f32_e32 v143, v143
	v_pk_add_f32 v[150:151], v[150:151], 1.0 op_sel_hi:[1,0]
	v_add_f32_e32 v143, 1.0, v143
	v_rcp_f32_e32 v144, v143
	v_lshlrev_b32_e32 v143, 16, v147
	v_mul_f32_e32 v143, 0xbfb8aa3b, v143
	v_exp_f32_e32 v146, v143
	v_and_b32_e32 v143, 0xffff0000, v145
	v_mul_f32_e32 v143, 0xbfb8aa3b, v143
	v_exp_f32_e32 v143, v143
	v_pk_mul_f32 v[148:149], v[148:149], v[150:151]
	v_add_f32_e32 v143, 1.0, v143
	v_rcp_f32_e32 v145, v143
	v_and_b32_e32 v143, 0xffff0000, v147
	v_mul_f32_e32 v143, 0xbfb8aa3b, v143
	v_exp_f32_e32 v147, v143
	s_nop 0
	v_lshlrev_b32_e32 v143, 16, v138
	v_and_b32_e32 v138, 0xffff0000, v138
	v_mul_f32_e32 v138, 0xbfb8aa3b, v138
	v_exp_f32_e32 v138, v138
	v_pk_add_f32 v[146:147], v[146:147], 1.0 op_sel_hi:[1,0]
	v_mul_f32_e32 v143, 0xbfb8aa3b, v143
	v_pk_mul_f32 v[144:145], v[144:145], v[146:147]
	v_add_f32_e32 v138, 1.0, v138
	v_pk_mul_f32 v[40:41], v[40:41], v[144:145]
	v_rcp_f32_e32 v145, v138
	s_nop 0
	v_and_b32_e32 v138, 0xffff0000, v140
	v_exp_f32_e32 v143, v143
	v_mul_f32_e32 v138, 0xbfb8aa3b, v138
	v_exp_f32_e32 v147, v138
	v_lshlrev_b32_e32 v138, 16, v139
	v_and_b32_e32 v139, 0xffff0000, v139
	v_mul_f32_e32 v138, 0xbfb8aa3b, v138
	v_mul_f32_e32 v139, 0xbfb8aa3b, v139
	v_exp_f32_e32 v138, v138
	v_exp_f32_e32 v139, v139
	v_add_f32_e32 v143, 1.0, v143
	v_rcp_f32_e32 v144, v143
	v_lshlrev_b32_e32 v143, 16, v140
	v_lshlrev_b32_e32 v140, 16, v141
	v_and_b32_e32 v141, 0xffff0000, v141
	v_mul_f32_e32 v140, 0xbfb8aa3b, v140
	v_mul_f32_e32 v141, 0xbfb8aa3b, v141
	v_add_f32_e32 v138, 1.0, v138
	v_exp_f32_e32 v140, v140
	v_add_f32_e32 v139, 1.0, v139
	v_exp_f32_e32 v141, v141
	v_rcp_f32_e32 v138, v138
	v_rcp_f32_e32 v139, v139
	v_mul_f32_e32 v143, 0xbfb8aa3b, v143
	v_exp_f32_e32 v146, v143
	v_pk_add_f32 v[140:141], v[140:141], 1.0 op_sel_hi:[1,0]
	v_pk_mul_f32 v[38:39], v[38:39], v[148:149]
	v_pk_mul_f32 v[138:139], v[138:139], v[140:141]
	v_pk_add_f32 v[146:147], v[146:147], 1.0 op_sel_hi:[1,0]
	v_pk_mul_f32 v[48:49], v[48:49], v[138:139]
	v_or_b32_e32 v138, 32, v142
	v_mad_i64_i32 v[140:141], s[26:27], v138, s35, v[136:137]
	v_pk_mul_f32 v[144:145], v[144:145], v[146:147]
	v_lshl_add_u64 v[138:139], v[140:141], 0, s[30:31]
	v_pk_mul_f32 v[46:47], v[46:47], v[144:145]
	v_lshl_add_u64 v[144:145], v[138:139], 0, v[0:1]
	s_waitcnt vmcnt(23)
	v_mov_b64_e32 v[144:145], v[230:231]
	v_lshl_add_u64 v[246:247], v[246:247], 0, s[88:89]
	global_load_dwordx2 v[230:231], v[246:247], off
	v_lshl_add_u64 v[140:141], v[140:141], 0, s[42:43]
	v_lshl_add_u64 v[146:147], v[140:141], 0, v[0:1]
	s_waitcnt vmcnt(23)
	v_mov_b64_e32 v[146:147], v[232:233]
	global_load_dwordx2 v[232:233], v[246:247], off offset:2048
	s_nop 0
	v_lshlrev_b32_e32 v143, 16, v144
	v_mul_f32_e32 v143, 0xbfb8aa3b, v143
	v_exp_f32_e32 v143, v143
	s_nop 0
	v_add_f32_e32 v143, 1.0, v143
	v_rcp_f32_e32 v148, v143
	s_nop 0
	v_lshlrev_b32_e32 v143, 16, v146
	v_mul_f32_e32 v143, 0xbfb8aa3b, v143
	v_exp_f32_e32 v150, v143
	v_and_b32_e32 v143, 0xffff0000, v144
	v_mul_f32_e32 v143, 0xbfb8aa3b, v143
	v_exp_f32_e32 v143, v143
	s_nop 0
	v_add_f32_e32 v143, 1.0, v143
	v_rcp_f32_e32 v149, v143
	v_and_b32_e32 v143, 0xffff0000, v146
	v_mul_f32_e32 v143, 0xbfb8aa3b, v143
	v_exp_f32_e32 v151, v143
	v_lshlrev_b32_e32 v143, 16, v145
	v_mul_f32_e32 v143, 0xbfb8aa3b, v143
	v_exp_f32_e32 v143, v143
	v_pk_add_f32 v[150:151], v[150:151], 1.0 op_sel_hi:[1,0]
	v_add_f32_e32 v143, 1.0, v143
	v_rcp_f32_e32 v144, v143
	v_lshlrev_b32_e32 v143, 16, v147
	v_mul_f32_e32 v143, 0xbfb8aa3b, v143
	v_exp_f32_e32 v146, v143
	v_and_b32_e32 v143, 0xffff0000, v145
	v_mul_f32_e32 v143, 0xbfb8aa3b, v143
	v_exp_f32_e32 v143, v143
	v_pk_mul_f32 v[148:149], v[148:149], v[150:151]
	v_add_f32_e32 v143, 1.0, v143
	v_rcp_f32_e32 v145, v143
	v_and_b32_e32 v143, 0xffff0000, v147
	v_mul_f32_e32 v143, 0xbfb8aa3b, v143
	v_exp_f32_e32 v147, v143
	v_pk_mul_f32 v[54:55], v[54:55], v[148:149]
	v_pk_add_f32 v[146:147], v[146:147], 1.0 op_sel_hi:[1,0]
	s_nop 0
	v_pk_mul_f32 v[144:145], v[144:145], v[146:147]
	v_lshl_add_u64 v[146:147], v[140:141], 0, v[134:135]
	v_pk_mul_f32 v[56:57], v[56:57], v[144:145]
	v_lshl_add_u64 v[144:145], v[138:139], 0, v[134:135]
	s_waitcnt vmcnt(23)
	v_mov_b64_e32 v[144:145], v[234:235]
	global_load_dwordx2 v[234:235], v[246:247], off offset:32
	s_nop 0
	s_waitcnt vmcnt(23)
; DI float bflo(unsigned u) { return __uint_as_float(u << 16); }
; DI float bfhi(unsigned u) { return __uint_as_float(u & 0xffff0000u); }
; DI float sigmoidf(float x) { return __builtin_amdgcn_rcpf(1.f + __expf(-x)); }
; DI float inv_sigmoidf(float x) { return 1.f + __expf(-x); }
; DI int TID8() { int t = threadIdx.x; asm volatile("" : "+v"(t)); return t; }
; template <class E>
; DI void gemm8_epi(f32x4 (&acc)[8][4], int m0, int n0, E e) {
;   const int tid = TID8(), lane = tid & 63, w = tid >> 6;
;   const int wm = w >> 2, wn = w & 3;
; #pragma unroll
;   for (int i = 0; i < 8; ++i)
; #pragma unroll
;     for (int j = 0; j < 4; ++j) {
;       const int m = m0 + wm * 128 + i * 16 + (lane & 15);
;       const int n = n0 + wn * 64 + j * 16 + (lane >> 4) * 4;
;       e(m, n, acc[i][j]);
;     }
; }
; __global__ void __launch_bounds__(512, 2) mega(Params p) {
;     ...
;       gemm8_epi(acc8, m0, n0, [&](int m, int n, f32x4& a) {
;         uint2 ua = *(const uint2*)(z + (size_t)m * ZS + C_MA + n);
;         uint2 ub = *(const uint2*)(z + (size_t)m * ZS + C_MB + n);
;         a[0] *= sigmoidf(bflo(ua.x)) * inv_sigmoidf(bflo(ub.x));
;         a[1] *= sigmoidf(bfhi(ua.x)) * inv_sigmoidf(bfhi(ub.x));
;         a[2] *= sigmoidf(bflo(ua.y)) * inv_sigmoidf(bflo(ub.y));
;         a[3] *= sigmoidf(bfhi(ua.y)) * inv_sigmoidf(bfhi(ub.y));
;       });
	v_mov_b64_e32 v[146:147], v[236:237]
	global_load_dwordx2 v[236:237], v[246:247], off offset:2080
	s_nop 0
	v_lshlrev_b32_e32 v143, 16, v144
	v_mul_f32_e32 v143, 0xbfb8aa3b, v143
	v_exp_f32_e32 v143, v143
	s_nop 0
	v_add_f32_e32 v143, 1.0, v143
	v_rcp_f32_e32 v148, v143
	s_nop 0
	v_lshlrev_b32_e32 v143, 16, v146
	v_mul_f32_e32 v143, 0xbfb8aa3b, v143
	v_exp_f32_e32 v150, v143
	v_and_b32_e32 v143, 0xffff0000, v144
	v_mul_f32_e32 v143, 0xbfb8aa3b, v143
	v_exp_f32_e32 v143, v143
	s_nop 0
	v_add_f32_e32 v143, 1.0, v143
	v_rcp_f32_e32 v149, v143
	v_and_b32_e32 v143, 0xffff0000, v146
	v_mul_f32_e32 v143, 0xbfb8aa3b, v143
	v_exp_f32_e32 v151, v143
	v_lshlrev_b32_e32 v143, 16, v145
	v_mul_f32_e32 v143, 0xbfb8aa3b, v143
	v_exp_f32_e32 v143, v143
	v_pk_add_f32 v[150:151], v[150:151], 1.0 op_sel_hi:[1,0]
	v_add_f32_e32 v143, 1.0, v143
	v_rcp_f32_e32 v144, v143
	v_lshlrev_b32_e32 v143, 16, v147
	v_mul_f32_e32 v143, 0xbfb8aa3b, v143
	v_exp_f32_e32 v146, v143
	v_and_b32_e32 v143, 0xffff0000, v145
	v_mul_f32_e32 v143, 0xbfb8aa3b, v143
	v_exp_f32_e32 v143, v143
	v_pk_mul_f32 v[148:149], v[148:149], v[150:151]
	v_add_f32_e32 v143, 1.0, v143
	v_rcp_f32_e32 v145, v143
	v_and_b32_e32 v143, 0xffff0000, v147
	v_mul_f32_e32 v143, 0xbfb8aa3b, v143
	v_exp_f32_e32 v147, v143
	v_pk_mul_f32 v[62:63], v[62:63], v[148:149]
	v_pk_add_f32 v[146:147], v[146:147], 1.0 op_sel_hi:[1,0]
	s_nop 0
	v_pk_mul_f32 v[144:145], v[144:145], v[146:147]
	v_lshl_add_u64 v[146:147], v[140:141], 0, v[132:133]
	v_pk_mul_f32 v[64:65], v[64:65], v[144:145]
	v_lshl_add_u64 v[144:145], v[138:139], 0, v[132:133]
	s_waitcnt vmcnt(23)
	v_mov_b64_e32 v[144:145], v[238:239]
	global_load_dwordx2 v[238:239], v[246:247], off offset:64
	v_lshl_add_u64 v[138:139], v[138:139], 0, v[130:131]
	s_waitcnt vmcnt(23)
	v_mov_b64_e32 v[146:147], v[240:241]
	global_load_dwordx2 v[240:241], v[246:247], off offset:2112
	v_lshl_add_u64 v[140:141], v[140:141], 0, v[130:131]
	s_waitcnt vmcnt(23)
	v_mov_b64_e32 v[138:139], v[242:243]
	global_load_dwordx2 v[242:243], v[246:247], off offset:96
	s_nop 0
	s_waitcnt vmcnt(23)
	v_mov_b64_e32 v[140:141], v[244:245]
	global_load_dwordx2 v[244:245], v[246:247], off offset:2144
	s_nop 0
	v_lshlrev_b32_e32 v143, 16, v144
	v_mul_f32_e32 v143, 0xbfb8aa3b, v143
	v_exp_f32_e32 v143, v143
	s_nop 0
	v_add_f32_e32 v143, 1.0, v143
	v_rcp_f32_e32 v148, v143
	s_nop 0
	v_lshlrev_b32_e32 v143, 16, v146
	v_mul_f32_e32 v143, 0xbfb8aa3b, v143
	v_exp_f32_e32 v150, v143
	v_and_b32_e32 v143, 0xffff0000, v144
	v_mul_f32_e32 v143, 0xbfb8aa3b, v143
	v_exp_f32_e32 v143, v143
	s_nop 0
	v_add_f32_e32 v143, 1.0, v143
	v_rcp_f32_e32 v149, v143
	v_and_b32_e32 v143, 0xffff0000, v146
	v_mul_f32_e32 v143, 0xbfb8aa3b, v143
	v_exp_f32_e32 v151, v143
	v_lshlrev_b32_e32 v143, 16, v145
	v_mul_f32_e32 v143, 0xbfb8aa3b, v143
	v_exp_f32_e32 v143, v143
	v_pk_add_f32 v[150:151], v[150:151], 1.0 op_sel_hi:[1,0]
	v_add_f32_e32 v143, 1.0, v143
	v_rcp_f32_e32 v144, v143
	v_lshlrev_b32_e32 v143, 16, v147
	v_mul_f32_e32 v143, 0xbfb8aa3b, v143
	v_exp_f32_e32 v146, v143
	v_and_b32_e32 v143, 0xffff0000, v145
	v_mul_f32_e32 v143, 0xbfb8aa3b, v143
	v_exp_f32_e32 v143, v143
	v_pk_mul_f32 v[148:149], v[148:149], v[150:151]
	v_add_f32_e32 v143, 1.0, v143
	v_rcp_f32_e32 v145, v143
	v_and_b32_e32 v143, 0xffff0000, v147
	v_mul_f32_e32 v143, 0xbfb8aa3b, v143
	v_exp_f32_e32 v147, v143
	s_nop 0
	v_lshlrev_b32_e32 v143, 16, v138
	v_and_b32_e32 v138, 0xffff0000, v138
	v_mul_f32_e32 v138, 0xbfb8aa3b, v138
	v_exp_f32_e32 v138, v138
	v_pk_add_f32 v[146:147], v[146:147], 1.0 op_sel_hi:[1,0]
	v_mul_f32_e32 v143, 0xbfb8aa3b, v143
	v_pk_mul_f32 v[144:145], v[144:145], v[146:147]
	v_add_f32_e32 v138, 1.0, v138
	v_pk_mul_f32 v[72:73], v[72:73], v[144:145]
	v_rcp_f32_e32 v145, v138
	s_nop 0
	v_and_b32_e32 v138, 0xffff0000, v140
	v_exp_f32_e32 v143, v143
	v_mul_f32_e32 v138, 0xbfb8aa3b, v138
	v_exp_f32_e32 v147, v138
	v_lshlrev_b32_e32 v138, 16, v139
	v_and_b32_e32 v139, 0xffff0000, v139
	v_mul_f32_e32 v138, 0xbfb8aa3b, v138
	v_mul_f32_e32 v139, 0xbfb8aa3b, v139
	v_exp_f32_e32 v138, v138
	v_exp_f32_e32 v139, v139
	v_add_f32_e32 v143, 1.0, v143
	v_rcp_f32_e32 v144, v143
	v_lshlrev_b32_e32 v143, 16, v140
	v_lshlrev_b32_e32 v140, 16, v141
	v_and_b32_e32 v141, 0xffff0000, v141
	v_mul_f32_e32 v140, 0xbfb8aa3b, v140
	v_mul_f32_e32 v141, 0xbfb8aa3b, v141
	v_add_f32_e32 v138, 1.0, v138
	v_exp_f32_e32 v140, v140
	v_add_f32_e32 v139, 1.0, v139
	v_exp_f32_e32 v141, v141
	v_rcp_f32_e32 v138, v138
	v_rcp_f32_e32 v139, v139
	v_mul_f32_e32 v143, 0xbfb8aa3b, v143
	v_exp_f32_e32 v146, v143
	v_pk_add_f32 v[140:141], v[140:141], 1.0 op_sel_hi:[1,0]
	v_pk_mul_f32 v[70:71], v[70:71], v[148:149]
	v_pk_mul_f32 v[138:139], v[138:139], v[140:141]
	v_pk_add_f32 v[146:147], v[146:147], 1.0 op_sel_hi:[1,0]
	v_pk_mul_f32 v[80:81], v[80:81], v[138:139]
	v_or_b32_e32 v138, 48, v142
	v_mad_i64_i32 v[140:141], s[26:27], v138, s35, v[136:137]
	v_pk_mul_f32 v[144:145], v[144:145], v[146:147]
	v_lshl_add_u64 v[138:139], v[140:141], 0, s[30:31]
	v_pk_mul_f32 v[78:79], v[78:79], v[144:145]
	v_lshl_add_u64 v[144:145], v[138:139], 0, v[0:1]
	s_waitcnt vmcnt(23)
	v_mov_b64_e32 v[144:145], v[198:199]
	v_lshl_add_u64 v[246:247], v[246:247], 0, s[88:89]
	global_load_dwordx2 v[198:199], v[246:247], off
	v_lshl_add_u64 v[140:141], v[140:141], 0, s[42:43]
	v_lshl_add_u64 v[146:147], v[140:141], 0, v[0:1]
	s_waitcnt vmcnt(23)
; DI float bflo(unsigned u) { return __uint_as_float(u << 16); }
; DI float bfhi(unsigned u) { return __uint_as_float(u & 0xffff0000u); }
; DI float sigmoidf(float x) { return __builtin_amdgcn_rcpf(1.f + __expf(-x)); }
; DI float inv_sigmoidf(float x) { return 1.f + __expf(-x); }
; DI int TID8() { int t = threadIdx.x; asm volatile("" : "+v"(t)); return t; }
; template <class E>
; DI void gemm8_epi(f32x4 (&acc)[8][4], int m0, int n0, E e) {
;   const int tid = TID8(), lane = tid & 63, w = tid >> 6;
;   const int wm = w >> 2, wn = w & 3;
; #pragma unroll
;   for (int i = 0; i < 8; ++i)
; #pragma unroll
;     for (int j = 0; j < 4; ++j) {
;       const int m = m0 + wm * 128 + i * 16 + (lane & 15);
;       const int n = n0 + wn * 64 + j * 16 + (lane >> 4) * 4;
;       e(m, n, acc[i][j]);
;     }
; }
; __global__ void __launch_bounds__(512, 2) mega(Params p) {
;     ...
;       gemm8_epi(acc8, m0, n0, [&](int m, int n, f32x4& a) {
;         uint2 ua = *(const uint2*)(z + (size_t)m * ZS + C_MA + n);
;         uint2 ub = *(const uint2*)(z + (size_t)m * ZS + C_MB + n);
;         a[0] *= sigmoidf(bflo(ua.x)) * inv_sigmoidf(bflo(ub.x));
;         a[1] *= sigmoidf(bfhi(ua.x)) * inv_sigmoidf(bfhi(ub.x));
;         a[2] *= sigmoidf(bflo(ua.y)) * inv_sigmoidf(bflo(ub.y));
;         a[3] *= sigmoidf(bfhi(ua.y)) * inv_sigmoidf(bfhi(ub.y));
;       });
	v_mov_b64_e32 v[146:147], v[200:201]
	global_load_dwordx2 v[200:201], v[246:247], off offset:2048
	s_nop 0
	v_lshlrev_b32_e32 v143, 16, v144
	v_mul_f32_e32 v143, 0xbfb8aa3b, v143
	v_exp_f32_e32 v143, v143
	s_nop 0
	v_add_f32_e32 v143, 1.0, v143
	v_rcp_f32_e32 v148, v143
	s_nop 0
	v_lshlrev_b32_e32 v143, 16, v146
	v_mul_f32_e32 v143, 0xbfb8aa3b, v143
	v_exp_f32_e32 v150, v143
	v_and_b32_e32 v143, 0xffff0000, v144
	v_mul_f32_e32 v143, 0xbfb8aa3b, v143
	v_exp_f32_e32 v143, v143
	s_nop 0
	v_add_f32_e32 v143, 1.0, v143
	v_rcp_f32_e32 v149, v143
	v_and_b32_e32 v143, 0xffff0000, v146
	v_mul_f32_e32 v143, 0xbfb8aa3b, v143
	v_exp_f32_e32 v151, v143
	v_lshlrev_b32_e32 v143, 16, v145
	v_mul_f32_e32 v143, 0xbfb8aa3b, v143
	v_exp_f32_e32 v143, v143
	v_pk_add_f32 v[150:151], v[150:151], 1.0 op_sel_hi:[1,0]
	v_add_f32_e32 v143, 1.0, v143
	v_rcp_f32_e32 v144, v143
	v_lshlrev_b32_e32 v143, 16, v147
	v_mul_f32_e32 v143, 0xbfb8aa3b, v143
	v_exp_f32_e32 v146, v143
	v_and_b32_e32 v143, 0xffff0000, v145
	v_mul_f32_e32 v143, 0xbfb8aa3b, v143
	v_exp_f32_e32 v143, v143
	v_pk_mul_f32 v[148:149], v[148:149], v[150:151]
	v_add_f32_e32 v143, 1.0, v143
	v_rcp_f32_e32 v145, v143
	v_and_b32_e32 v143, 0xffff0000, v147
	v_mul_f32_e32 v143, 0xbfb8aa3b, v143
	v_exp_f32_e32 v147, v143
	v_pk_mul_f32 v[86:87], v[86:87], v[148:149]
	v_pk_add_f32 v[146:147], v[146:147], 1.0 op_sel_hi:[1,0]
	s_nop 0
	v_pk_mul_f32 v[144:145], v[144:145], v[146:147]
	v_lshl_add_u64 v[146:147], v[140:141], 0, v[134:135]
	v_pk_mul_f32 v[88:89], v[88:89], v[144:145]
	v_lshl_add_u64 v[144:145], v[138:139], 0, v[134:135]
	s_waitcnt vmcnt(23)
	v_mov_b64_e32 v[144:145], v[202:203]
	global_load_dwordx2 v[202:203], v[246:247], off offset:32
	s_nop 0
	s_waitcnt vmcnt(23)
	v_mov_b64_e32 v[146:147], v[204:205]
	global_load_dwordx2 v[204:205], v[246:247], off offset:2080
	s_nop 0
	v_lshlrev_b32_e32 v143, 16, v144
	v_mul_f32_e32 v143, 0xbfb8aa3b, v143
	v_exp_f32_e32 v143, v143
	s_nop 0
	v_add_f32_e32 v143, 1.0, v143
	v_rcp_f32_e32 v148, v143
	s_nop 0
	v_lshlrev_b32_e32 v143, 16, v146
	v_mul_f32_e32 v143, 0xbfb8aa3b, v143
	v_exp_f32_e32 v150, v143
	v_and_b32_e32 v143, 0xffff0000, v144
	v_mul_f32_e32 v143, 0xbfb8aa3b, v143
	v_exp_f32_e32 v143, v143
	s_nop 0
	v_add_f32_e32 v143, 1.0, v143
	v_rcp_f32_e32 v149, v143
	v_and_b32_e32 v143, 0xffff0000, v146
	v_mul_f32_e32 v143, 0xbfb8aa3b, v143
	v_exp_f32_e32 v151, v143
	v_lshlrev_b32_e32 v143, 16, v145
	v_mul_f32_e32 v143, 0xbfb8aa3b, v143
	v_exp_f32_e32 v143, v143
	v_pk_add_f32 v[150:151], v[150:151], 1.0 op_sel_hi:[1,0]
	v_add_f32_e32 v143, 1.0, v143
	v_rcp_f32_e32 v144, v143
	v_lshlrev_b32_e32 v143, 16, v147
	v_mul_f32_e32 v143, 0xbfb8aa3b, v143
	v_exp_f32_e32 v146, v143
	v_and_b32_e32 v143, 0xffff0000, v145
	v_mul_f32_e32 v143, 0xbfb8aa3b, v143
	v_exp_f32_e32 v143, v143
	v_pk_mul_f32 v[148:149], v[148:149], v[150:151]
	v_add_f32_e32 v143, 1.0, v143
	v_rcp_f32_e32 v145, v143
	v_and_b32_e32 v143, 0xffff0000, v147
	v_mul_f32_e32 v143, 0xbfb8aa3b, v143
	v_exp_f32_e32 v147, v143
	v_pk_mul_f32 v[94:95], v[94:95], v[148:149]
	v_pk_add_f32 v[146:147], v[146:147], 1.0 op_sel_hi:[1,0]
	s_nop 0
	v_pk_mul_f32 v[144:145], v[144:145], v[146:147]
	v_lshl_add_u64 v[146:147], v[140:141], 0, v[132:133]
	v_pk_mul_f32 v[96:97], v[96:97], v[144:145]
	v_lshl_add_u64 v[144:145], v[138:139], 0, v[132:133]
	s_waitcnt vmcnt(23)
	v_mov_b64_e32 v[144:145], v[206:207]
	global_load_dwordx2 v[206:207], v[246:247], off offset:64
	v_lshl_add_u64 v[138:139], v[138:139], 0, v[130:131]
	s_waitcnt vmcnt(23)
	v_mov_b64_e32 v[146:147], v[208:209]
	global_load_dwordx2 v[208:209], v[246:247], off offset:2112
	v_lshl_add_u64 v[140:141], v[140:141], 0, v[130:131]
	s_waitcnt vmcnt(23)
	v_mov_b64_e32 v[138:139], v[210:211]
	global_load_dwordx2 v[210:211], v[246:247], off offset:96
	s_nop 0
	s_waitcnt vmcnt(23)
	v_mov_b64_e32 v[140:141], v[212:213]
	global_load_dwordx2 v[212:213], v[246:247], off offset:2144
	s_nop 0
	v_lshlrev_b32_e32 v143, 16, v144
	v_mul_f32_e32 v143, 0xbfb8aa3b, v143
	v_exp_f32_e32 v143, v143
	s_nop 0
	v_add_f32_e32 v143, 1.0, v143
	v_rcp_f32_e32 v148, v143
	s_nop 0
	v_lshlrev_b32_e32 v143, 16, v146
	v_mul_f32_e32 v143, 0xbfb8aa3b, v143
	v_exp_f32_e32 v150, v143
	v_and_b32_e32 v143, 0xffff0000, v144
	v_mul_f32_e32 v143, 0xbfb8aa3b, v143
	v_exp_f32_e32 v143, v143
	s_nop 0
	v_add_f32_e32 v143, 1.0, v143
	v_rcp_f32_e32 v149, v143
	v_and_b32_e32 v143, 0xffff0000, v146
	v_mul_f32_e32 v143, 0xbfb8aa3b, v143
	v_exp_f32_e32 v151, v143
	v_lshlrev_b32_e32 v143, 16, v145
	v_mul_f32_e32 v143, 0xbfb8aa3b, v143
	v_exp_f32_e32 v143, v143
	v_pk_add_f32 v[150:151], v[150:151], 1.0 op_sel_hi:[1,0]
	v_add_f32_e32 v143, 1.0, v143
	v_rcp_f32_e32 v144, v143
	v_lshlrev_b32_e32 v143, 16, v147
	v_mul_f32_e32 v143, 0xbfb8aa3b, v143
	v_exp_f32_e32 v146, v143
	v_and_b32_e32 v143, 0xffff0000, v145
	v_mul_f32_e32 v143, 0xbfb8aa3b, v143
	v_exp_f32_e32 v143, v143
	v_pk_mul_f32 v[148:149], v[148:149], v[150:151]
	v_add_f32_e32 v143, 1.0, v143
	v_rcp_f32_e32 v145, v143
	v_and_b32_e32 v143, 0xffff0000, v147
	v_mul_f32_e32 v143, 0xbfb8aa3b, v143
	v_exp_f32_e32 v147, v143
	s_nop 0
	v_lshlrev_b32_e32 v143, 16, v138
	v_and_b32_e32 v138, 0xffff0000, v138
	v_mul_f32_e32 v138, 0xbfb8aa3b, v138
	v_exp_f32_e32 v138, v138
	v_pk_add_f32 v[146:147], v[146:147], 1.0 op_sel_hi:[1,0]
	v_mul_f32_e32 v143, 0xbfb8aa3b, v143
	v_pk_mul_f32 v[144:145], v[144:145], v[146:147]
	v_add_f32_e32 v138, 1.0, v138
	v_pk_mul_f32 v[104:105], v[104:105], v[144:145]
	v_rcp_f32_e32 v145, v138
	s_nop 0
	v_and_b32_e32 v138, 0xffff0000, v140
	v_exp_f32_e32 v143, v143
	v_mul_f32_e32 v138, 0xbfb8aa3b, v138
	v_exp_f32_e32 v147, v138
	v_lshlrev_b32_e32 v138, 16, v139
	v_and_b32_e32 v139, 0xffff0000, v139
	v_mul_f32_e32 v138, 0xbfb8aa3b, v138
	v_mul_f32_e32 v139, 0xbfb8aa3b, v139
	v_exp_f32_e32 v138, v138
	v_exp_f32_e32 v139, v139
	v_add_f32_e32 v143, 1.0, v143
	v_rcp_f32_e32 v144, v143
	v_lshlrev_b32_e32 v143, 16, v140
	v_lshlrev_b32_e32 v140, 16, v141
	v_and_b32_e32 v141, 0xffff0000, v141
	v_mul_f32_e32 v140, 0xbfb8aa3b, v140
	v_mul_f32_e32 v141, 0xbfb8aa3b, v141
	v_add_f32_e32 v138, 1.0, v138
	v_exp_f32_e32 v140, v140
	v_add_f32_e32 v139, 1.0, v139
	v_exp_f32_e32 v141, v141
	v_rcp_f32_e32 v138, v138
	v_rcp_f32_e32 v139, v139
	v_mul_f32_e32 v143, 0xbfb8aa3b, v143
	v_exp_f32_e32 v146, v143
	v_pk_add_f32 v[140:141], v[140:141], 1.0 op_sel_hi:[1,0]
	v_pk_mul_f32 v[102:103], v[102:103], v[148:149]
	v_pk_mul_f32 v[138:139], v[138:139], v[140:141]
	v_pk_add_f32 v[146:147], v[146:147], 1.0 op_sel_hi:[1,0]
	v_pk_mul_f32 v[112:113], v[112:113], v[138:139]
	v_or_b32_e32 v138, 64, v142
	v_mad_i64_i32 v[140:141], s[26:27], v138, s35, v[136:137]
	v_pk_mul_f32 v[144:145], v[144:145], v[146:147]
	v_lshl_add_u64 v[138:139], v[140:141], 0, s[30:31]
	v_pk_mul_f32 v[110:111], v[110:111], v[144:145]
	v_lshl_add_u64 v[144:145], v[138:139], 0, v[0:1]
	s_waitcnt vmcnt(23)
; DI float bflo(unsigned u) { return __uint_as_float(u << 16); }
; DI float bfhi(unsigned u) { return __uint_as_float(u & 0xffff0000u); }
; DI float sigmoidf(float x) { return __builtin_amdgcn_rcpf(1.f + __expf(-x)); }
; DI float inv_sigmoidf(float x) { return 1.f + __expf(-x); }
; DI int TID8() { int t = threadIdx.x; asm volatile("" : "+v"(t)); return t; }
; template <class E>
; DI void gemm8_epi(f32x4 (&acc)[8][4], int m0, int n0, E e) {
;   const int tid = TID8(), lane = tid & 63, w = tid >> 6;
;   const int wm = w >> 2, wn = w & 3;
; #pragma unroll
;   for (int i = 0; i < 8; ++i)
; #pragma unroll
;     for (int j = 0; j < 4; ++j) {
;       const int m = m0 + wm * 128 + i * 16 + (lane & 15);
;       const int n = n0 + wn * 64 + j * 16 + (lane >> 4) * 4;
;       e(m, n, acc[i][j]);
;     }
; }
; __global__ void __launch_bounds__(512, 2) mega(Params p) {
;     ...
;       gemm8_epi(acc8, m0, n0, [&](int m, int n, f32x4& a) {
;         uint2 ua = *(const uint2*)(z + (size_t)m * ZS + C_MA + n);
;         uint2 ub = *(const uint2*)(z + (size_t)m * ZS + C_MB + n);
;         a[0] *= sigmoidf(bflo(ua.x)) * inv_sigmoidf(bflo(ub.x));
;         a[1] *= sigmoidf(bfhi(ua.x)) * inv_sigmoidf(bfhi(ub.x));
;         a[2] *= sigmoidf(bflo(ua.y)) * inv_sigmoidf(bflo(ub.y));
;         a[3] *= sigmoidf(bfhi(ua.y)) * inv_sigmoidf(bfhi(ub.y));
;       });
	v_mov_b64_e32 v[144:145], v[214:215]
	v_lshl_add_u64 v[246:247], v[246:247], 0, s[88:89]
	global_load_dwordx2 v[214:215], v[246:247], off
	v_lshl_add_u64 v[140:141], v[140:141], 0, s[42:43]
	v_lshl_add_u64 v[146:147], v[140:141], 0, v[0:1]
	s_waitcnt vmcnt(23)
	v_mov_b64_e32 v[146:147], v[216:217]
	global_load_dwordx2 v[216:217], v[246:247], off offset:2048
	s_nop 0
	v_lshlrev_b32_e32 v143, 16, v144
	v_mul_f32_e32 v143, 0xbfb8aa3b, v143
	v_exp_f32_e32 v143, v143
	s_nop 0
	v_add_f32_e32 v143, 1.0, v143
	v_rcp_f32_e32 v148, v143
	s_nop 0
	v_lshlrev_b32_e32 v143, 16, v146
	v_mul_f32_e32 v143, 0xbfb8aa3b, v143
	v_exp_f32_e32 v150, v143
	v_and_b32_e32 v143, 0xffff0000, v144
	v_mul_f32_e32 v143, 0xbfb8aa3b, v143
	v_exp_f32_e32 v143, v143
	s_nop 0
	v_add_f32_e32 v143, 1.0, v143
	v_rcp_f32_e32 v149, v143
	v_and_b32_e32 v143, 0xffff0000, v146
	v_mul_f32_e32 v143, 0xbfb8aa3b, v143
	v_exp_f32_e32 v151, v143
	v_lshlrev_b32_e32 v143, 16, v145
	v_mul_f32_e32 v143, 0xbfb8aa3b, v143
	v_exp_f32_e32 v143, v143
	v_pk_add_f32 v[150:151], v[150:151], 1.0 op_sel_hi:[1,0]
	v_add_f32_e32 v143, 1.0, v143
	v_rcp_f32_e32 v144, v143
	v_lshlrev_b32_e32 v143, 16, v147
	v_mul_f32_e32 v143, 0xbfb8aa3b, v143
	v_exp_f32_e32 v146, v143
	v_and_b32_e32 v143, 0xffff0000, v145
	v_mul_f32_e32 v143, 0xbfb8aa3b, v143
	v_exp_f32_e32 v143, v143
	v_pk_mul_f32 v[148:149], v[148:149], v[150:151]
	v_add_f32_e32 v143, 1.0, v143
	v_rcp_f32_e32 v145, v143
	v_and_b32_e32 v143, 0xffff0000, v147
	v_mul_f32_e32 v143, 0xbfb8aa3b, v143
	v_exp_f32_e32 v147, v143
	v_pk_mul_f32 v[118:119], v[118:119], v[148:149]
	v_pk_add_f32 v[146:147], v[146:147], 1.0 op_sel_hi:[1,0]
	s_nop 0
	v_pk_mul_f32 v[144:145], v[144:145], v[146:147]
	v_lshl_add_u64 v[146:147], v[140:141], 0, v[134:135]
	v_pk_mul_f32 v[120:121], v[120:121], v[144:145]
	v_lshl_add_u64 v[144:145], v[138:139], 0, v[134:135]
	s_waitcnt vmcnt(23)
	v_mov_b64_e32 v[144:145], v[218:219]
	global_load_dwordx2 v[218:219], v[246:247], off offset:32
	s_nop 0
	s_waitcnt vmcnt(23)
	v_mov_b64_e32 v[146:147], v[220:221]
	global_load_dwordx2 v[220:221], v[246:247], off offset:2080
	s_nop 0
	v_lshlrev_b32_e32 v143, 16, v144
	v_mul_f32_e32 v143, 0xbfb8aa3b, v143
	v_exp_f32_e32 v143, v143
	s_nop 0
	v_add_f32_e32 v143, 1.0, v143
	v_rcp_f32_e32 v148, v143
	s_nop 0
	v_lshlrev_b32_e32 v143, 16, v146
	v_mul_f32_e32 v143, 0xbfb8aa3b, v143
	v_exp_f32_e32 v150, v143
	v_and_b32_e32 v143, 0xffff0000, v144
	v_mul_f32_e32 v143, 0xbfb8aa3b, v143
	v_exp_f32_e32 v143, v143
	s_nop 0
	v_add_f32_e32 v143, 1.0, v143
	v_rcp_f32_e32 v149, v143
	v_and_b32_e32 v143, 0xffff0000, v146
	v_mul_f32_e32 v143, 0xbfb8aa3b, v143
	v_exp_f32_e32 v151, v143
	v_lshlrev_b32_e32 v143, 16, v145
	v_mul_f32_e32 v143, 0xbfb8aa3b, v143
	v_exp_f32_e32 v143, v143
	v_pk_add_f32 v[150:151], v[150:151], 1.0 op_sel_hi:[1,0]
	v_add_f32_e32 v143, 1.0, v143
	v_rcp_f32_e32 v144, v143
	v_lshlrev_b32_e32 v143, 16, v147
	v_mul_f32_e32 v143, 0xbfb8aa3b, v143
	v_exp_f32_e32 v146, v143
	v_and_b32_e32 v143, 0xffff0000, v145
	v_mul_f32_e32 v143, 0xbfb8aa3b, v143
	v_exp_f32_e32 v143, v143
	v_pk_mul_f32 v[148:149], v[148:149], v[150:151]
	v_add_f32_e32 v143, 1.0, v143
	v_rcp_f32_e32 v145, v143
	v_and_b32_e32 v143, 0xffff0000, v147
	v_mul_f32_e32 v143, 0xbfb8aa3b, v143
	v_exp_f32_e32 v147, v143
	v_pk_mul_f32 v[126:127], v[126:127], v[148:149]
	v_pk_add_f32 v[146:147], v[146:147], 1.0 op_sel_hi:[1,0]
	s_nop 0
	v_pk_mul_f32 v[144:145], v[144:145], v[146:147]
	v_lshl_add_u64 v[146:147], v[140:141], 0, v[132:133]
	v_pk_mul_f32 v[128:129], v[128:129], v[144:145]
	v_lshl_add_u64 v[144:145], v[138:139], 0, v[132:133]
	s_waitcnt vmcnt(23)
	v_mov_b64_e32 v[144:145], v[222:223]
	global_load_dwordx2 v[222:223], v[246:247], off offset:64
	v_lshl_add_u64 v[138:139], v[138:139], 0, v[130:131]
	s_waitcnt vmcnt(23)
	v_mov_b64_e32 v[146:147], v[224:225]
	global_load_dwordx2 v[224:225], v[246:247], off offset:2112
	v_lshl_add_u64 v[140:141], v[140:141], 0, v[130:131]
	s_waitcnt vmcnt(23)
	v_mov_b64_e32 v[138:139], v[226:227]
	global_load_dwordx2 v[226:227], v[246:247], off offset:96
	s_nop 0
	s_waitcnt vmcnt(23)
	v_mov_b64_e32 v[140:141], v[228:229]
	global_load_dwordx2 v[228:229], v[246:247], off offset:2144
	s_nop 0
	v_lshlrev_b32_e32 v143, 16, v144
	v_mul_f32_e32 v143, 0xbfb8aa3b, v143
	v_exp_f32_e32 v143, v143
	s_nop 0
	v_add_f32_e32 v143, 1.0, v143
	v_rcp_f32_e32 v148, v143
	s_nop 0
	v_lshlrev_b32_e32 v143, 16, v146
	v_mul_f32_e32 v143, 0xbfb8aa3b, v143
	v_exp_f32_e32 v150, v143
	v_and_b32_e32 v143, 0xffff0000, v144
	v_mul_f32_e32 v143, 0xbfb8aa3b, v143
	v_exp_f32_e32 v143, v143
	s_nop 0
	v_add_f32_e32 v143, 1.0, v143
	v_rcp_f32_e32 v149, v143
	v_and_b32_e32 v143, 0xffff0000, v146
	v_mul_f32_e32 v143, 0xbfb8aa3b, v143
	v_exp_f32_e32 v151, v143
	v_lshlrev_b32_e32 v143, 16, v145
	v_mul_f32_e32 v143, 0xbfb8aa3b, v143
	v_exp_f32_e32 v143, v143
	v_pk_add_f32 v[150:151], v[150:151], 1.0 op_sel_hi:[1,0]
	v_add_f32_e32 v143, 1.0, v143
	v_rcp_f32_e32 v144, v143
	v_lshlrev_b32_e32 v143, 16, v147
	v_mul_f32_e32 v143, 0xbfb8aa3b, v143
	v_exp_f32_e32 v146, v143
	v_and_b32_e32 v143, 0xffff0000, v145
	v_mul_f32_e32 v143, 0xbfb8aa3b, v143
	v_exp_f32_e32 v143, v143
	v_pk_mul_f32 v[148:149], v[148:149], v[150:151]
	v_add_f32_e32 v143, 1.0, v143
	v_rcp_f32_e32 v145, v143
	v_and_b32_e32 v143, 0xffff0000, v147
	v_mul_f32_e32 v143, 0xbfb8aa3b, v143
	v_exp_f32_e32 v147, v143
	s_nop 0
	v_lshlrev_b32_e32 v143, 16, v138
	v_and_b32_e32 v138, 0xffff0000, v138
	v_mul_f32_e32 v138, 0xbfb8aa3b, v138
	v_exp_f32_e32 v138, v138
	v_pk_add_f32 v[146:147], v[146:147], 1.0 op_sel_hi:[1,0]
	v_mul_f32_e32 v143, 0xbfb8aa3b, v143
	v_pk_mul_f32 v[144:145], v[144:145], v[146:147]
; DI float bflo(unsigned u) { return __uint_as_float(u << 16); }
; DI float bfhi(unsigned u) { return __uint_as_float(u & 0xffff0000u); }
; DI float sigmoidf(float x) { return __builtin_amdgcn_rcpf(1.f + __expf(-x)); }
; DI float inv_sigmoidf(float x) { return 1.f + __expf(-x); }
; DI int TID8() { int t = threadIdx.x; asm volatile("" : "+v"(t)); return t; }
; template <class E>
; DI void gemm8_epi(f32x4 (&acc)[8][4], int m0, int n0, E e) {
;   const int tid = TID8(), lane = tid & 63, w = tid >> 6;
;   const int wm = w >> 2, wn = w & 3;
; #pragma unroll
;   for (int i = 0; i < 8; ++i)
; #pragma unroll
;     for (int j = 0; j < 4; ++j) {
;       const int m = m0 + wm * 128 + i * 16 + (lane & 15);
;       const int n = n0 + wn * 64 + j * 16 + (lane >> 4) * 4;
;       e(m, n, acc[i][j]);
;     }
; }
; __global__ void __launch_bounds__(512, 2) mega(Params p) {
;     ...
;       gemm8_epi(acc8, m0, n0, [&](int m, int n, f32x4& a) {
;         uint2 ua = *(const uint2*)(z + (size_t)m * ZS + C_MA + n);
;         uint2 ub = *(const uint2*)(z + (size_t)m * ZS + C_MB + n);
;         a[0] *= sigmoidf(bflo(ua.x)) * inv_sigmoidf(bflo(ub.x));
;         a[1] *= sigmoidf(bfhi(ua.x)) * inv_sigmoidf(bfhi(ub.x));
;         a[2] *= sigmoidf(bflo(ua.y)) * inv_sigmoidf(bflo(ub.y));
;         a[3] *= sigmoidf(bfhi(ua.y)) * inv_sigmoidf(bfhi(ub.y));
;       });
	v_add_f32_e32 v138, 1.0, v138
	v_pk_mul_f32 v[124:125], v[124:125], v[144:145]
	v_rcp_f32_e32 v145, v138
	s_nop 0
	v_and_b32_e32 v138, 0xffff0000, v140
	v_exp_f32_e32 v143, v143
	v_mul_f32_e32 v138, 0xbfb8aa3b, v138
	v_exp_f32_e32 v147, v138
	v_lshlrev_b32_e32 v138, 16, v139
	v_and_b32_e32 v139, 0xffff0000, v139
	v_mul_f32_e32 v138, 0xbfb8aa3b, v138
	v_mul_f32_e32 v139, 0xbfb8aa3b, v139
	v_exp_f32_e32 v138, v138
	v_exp_f32_e32 v139, v139
	v_add_f32_e32 v143, 1.0, v143
	v_rcp_f32_e32 v144, v143
	v_lshlrev_b32_e32 v143, 16, v140
	v_lshlrev_b32_e32 v140, 16, v141
	v_and_b32_e32 v141, 0xffff0000, v141
	v_mul_f32_e32 v140, 0xbfb8aa3b, v140
	v_mul_f32_e32 v141, 0xbfb8aa3b, v141
	v_add_f32_e32 v138, 1.0, v138
	v_exp_f32_e32 v140, v140
	v_add_f32_e32 v139, 1.0, v139
	v_exp_f32_e32 v141, v141
	v_rcp_f32_e32 v138, v138
	v_rcp_f32_e32 v139, v139
	v_mul_f32_e32 v143, 0xbfb8aa3b, v143
	v_exp_f32_e32 v146, v143
	v_pk_add_f32 v[140:141], v[140:141], 1.0 op_sel_hi:[1,0]
	v_pk_mul_f32 v[122:123], v[122:123], v[148:149]
	v_pk_mul_f32 v[138:139], v[138:139], v[140:141]
	v_pk_add_f32 v[146:147], v[146:147], 1.0 op_sel_hi:[1,0]
	v_pk_mul_f32 v[116:117], v[116:117], v[138:139]
	v_or_b32_e32 v138, 0x50, v142
	v_mad_i64_i32 v[140:141], s[26:27], v138, s35, v[136:137]
	v_pk_mul_f32 v[144:145], v[144:145], v[146:147]
	v_lshl_add_u64 v[138:139], v[140:141], 0, s[30:31]
	v_pk_mul_f32 v[114:115], v[114:115], v[144:145]
	v_lshl_add_u64 v[144:145], v[138:139], 0, v[0:1]
	s_waitcnt vmcnt(23)
	v_mov_b64_e32 v[144:145], v[230:231]
	v_lshl_add_u64 v[140:141], v[140:141], 0, s[42:43]
	v_lshl_add_u64 v[146:147], v[140:141], 0, v[0:1]
	s_waitcnt vmcnt(22)
	v_mov_b64_e32 v[146:147], v[232:233]
	s_nop 0
	v_lshlrev_b32_e32 v143, 16, v144
	v_mul_f32_e32 v143, 0xbfb8aa3b, v143
	v_exp_f32_e32 v143, v143
	s_nop 0
	v_add_f32_e32 v143, 1.0, v143
	v_rcp_f32_e32 v148, v143
	s_nop 0
	v_lshlrev_b32_e32 v143, 16, v146
	v_mul_f32_e32 v143, 0xbfb8aa3b, v143
	v_exp_f32_e32 v150, v143
	v_and_b32_e32 v143, 0xffff0000, v144
	v_mul_f32_e32 v143, 0xbfb8aa3b, v143
	v_exp_f32_e32 v143, v143
	s_nop 0
	v_add_f32_e32 v143, 1.0, v143
	v_rcp_f32_e32 v149, v143
	v_and_b32_e32 v143, 0xffff0000, v146
	v_mul_f32_e32 v143, 0xbfb8aa3b, v143
	v_exp_f32_e32 v151, v143
	v_lshlrev_b32_e32 v143, 16, v145
	v_mul_f32_e32 v143, 0xbfb8aa3b, v143
	v_exp_f32_e32 v143, v143
	v_pk_add_f32 v[150:151], v[150:151], 1.0 op_sel_hi:[1,0]
	v_add_f32_e32 v143, 1.0, v143
	v_rcp_f32_e32 v144, v143
	v_lshlrev_b32_e32 v143, 16, v147
	v_mul_f32_e32 v143, 0xbfb8aa3b, v143
	v_exp_f32_e32 v146, v143
	v_and_b32_e32 v143, 0xffff0000, v145
	v_mul_f32_e32 v143, 0xbfb8aa3b, v143
	v_exp_f32_e32 v143, v143
	v_pk_mul_f32 v[148:149], v[148:149], v[150:151]
	v_add_f32_e32 v143, 1.0, v143
	v_rcp_f32_e32 v145, v143
	v_and_b32_e32 v143, 0xffff0000, v147
	v_mul_f32_e32 v143, 0xbfb8aa3b, v143
	v_exp_f32_e32 v147, v143
	v_pk_mul_f32 v[106:107], v[106:107], v[148:149]
	v_pk_add_f32 v[146:147], v[146:147], 1.0 op_sel_hi:[1,0]
	s_nop 0
	v_pk_mul_f32 v[144:145], v[144:145], v[146:147]
	v_lshl_add_u64 v[146:147], v[140:141], 0, v[134:135]
	v_pk_mul_f32 v[108:109], v[108:109], v[144:145]
	v_lshl_add_u64 v[144:145], v[138:139], 0, v[134:135]
	s_waitcnt vmcnt(21)
	v_mov_b64_e32 v[144:145], v[234:235]
	s_nop 0
	s_waitcnt vmcnt(20)
	v_mov_b64_e32 v[146:147], v[236:237]
	s_nop 0
	v_lshlrev_b32_e32 v143, 16, v144
	v_mul_f32_e32 v143, 0xbfb8aa3b, v143
	v_exp_f32_e32 v143, v143
	s_nop 0
	v_add_f32_e32 v143, 1.0, v143
	v_rcp_f32_e32 v148, v143
	s_nop 0
	v_lshlrev_b32_e32 v143, 16, v146
	v_mul_f32_e32 v143, 0xbfb8aa3b, v143
	v_exp_f32_e32 v150, v143
	v_and_b32_e32 v143, 0xffff0000, v144
	v_mul_f32_e32 v143, 0xbfb8aa3b, v143
	v_exp_f32_e32 v143, v143
	s_nop 0
	v_add_f32_e32 v143, 1.0, v143
	v_rcp_f32_e32 v149, v143
	v_and_b32_e32 v143, 0xffff0000, v146
	v_mul_f32_e32 v143, 0xbfb8aa3b, v143
	v_exp_f32_e32 v151, v143
	v_lshlrev_b32_e32 v143, 16, v145
	v_mul_f32_e32 v143, 0xbfb8aa3b, v143
	v_exp_f32_e32 v143, v143
	v_pk_add_f32 v[150:151], v[150:151], 1.0 op_sel_hi:[1,0]
	v_add_f32_e32 v143, 1.0, v143
	v_rcp_f32_e32 v144, v143
	v_lshlrev_b32_e32 v143, 16, v147
	v_mul_f32_e32 v143, 0xbfb8aa3b, v143
	v_exp_f32_e32 v146, v143
	v_and_b32_e32 v143, 0xffff0000, v145
	v_mul_f32_e32 v143, 0xbfb8aa3b, v143
	v_exp_f32_e32 v143, v143
	v_pk_mul_f32 v[148:149], v[148:149], v[150:151]
	v_add_f32_e32 v143, 1.0, v143
	v_rcp_f32_e32 v145, v143
	v_and_b32_e32 v143, 0xffff0000, v147
	v_mul_f32_e32 v143, 0xbfb8aa3b, v143
	v_exp_f32_e32 v147, v143
	v_pk_mul_f32 v[98:99], v[98:99], v[148:149]
	v_pk_add_f32 v[146:147], v[146:147], 1.0 op_sel_hi:[1,0]
	s_nop 0
	v_pk_mul_f32 v[144:145], v[144:145], v[146:147]
	v_lshl_add_u64 v[146:147], v[140:141], 0, v[132:133]
	v_pk_mul_f32 v[100:101], v[100:101], v[144:145]
	v_lshl_add_u64 v[144:145], v[138:139], 0, v[132:133]
	s_waitcnt vmcnt(19)
	v_mov_b64_e32 v[144:145], v[238:239]
	v_lshl_add_u64 v[138:139], v[138:139], 0, v[130:131]
	s_waitcnt vmcnt(18)
	v_mov_b64_e32 v[146:147], v[240:241]
	v_lshl_add_u64 v[140:141], v[140:141], 0, v[130:131]
	s_waitcnt vmcnt(17)
	v_mov_b64_e32 v[138:139], v[242:243]
	s_nop 0
	s_waitcnt vmcnt(16)
; DI float bflo(unsigned u) { return __uint_as_float(u << 16); }
; DI float bfhi(unsigned u) { return __uint_as_float(u & 0xffff0000u); }
; DI float sigmoidf(float x) { return __builtin_amdgcn_rcpf(1.f + __expf(-x)); }
; DI float inv_sigmoidf(float x) { return 1.f + __expf(-x); }
; DI int TID8() { int t = threadIdx.x; asm volatile("" : "+v"(t)); return t; }
; template <class E>
; DI void gemm8_epi(f32x4 (&acc)[8][4], int m0, int n0, E e) {
;   const int tid = TID8(), lane = tid & 63, w = tid >> 6;
;   const int wm = w >> 2, wn = w & 3;
; #pragma unroll
;   for (int i = 0; i < 8; ++i)
; #pragma unroll
;     for (int j = 0; j < 4; ++j) {
;       const int m = m0 + wm * 128 + i * 16 + (lane & 15);
;       const int n = n0 + wn * 64 + j * 16 + (lane >> 4) * 4;
;       e(m, n, acc[i][j]);
;     }
; }
; __global__ void __launch_bounds__(512, 2) mega(Params p) {
;     ...
;       gemm8_epi(acc8, m0, n0, [&](int m, int n, f32x4& a) {
;         uint2 ua = *(const uint2*)(z + (size_t)m * ZS + C_MA + n);
;         uint2 ub = *(const uint2*)(z + (size_t)m * ZS + C_MB + n);
;         a[0] *= sigmoidf(bflo(ua.x)) * inv_sigmoidf(bflo(ub.x));
;         a[1] *= sigmoidf(bfhi(ua.x)) * inv_sigmoidf(bfhi(ub.x));
;         a[2] *= sigmoidf(bflo(ua.y)) * inv_sigmoidf(bflo(ub.y));
;         a[3] *= sigmoidf(bfhi(ua.y)) * inv_sigmoidf(bfhi(ub.y));
;       });
	v_mov_b64_e32 v[140:141], v[244:245]
	s_nop 0
	v_lshlrev_b32_e32 v143, 16, v144
	v_mul_f32_e32 v143, 0xbfb8aa3b, v143
	v_exp_f32_e32 v143, v143
	s_nop 0
	v_add_f32_e32 v143, 1.0, v143
	v_rcp_f32_e32 v148, v143
	s_nop 0
	v_lshlrev_b32_e32 v143, 16, v146
	v_mul_f32_e32 v143, 0xbfb8aa3b, v143
	v_exp_f32_e32 v150, v143
	v_and_b32_e32 v143, 0xffff0000, v144
	v_mul_f32_e32 v143, 0xbfb8aa3b, v143
	v_exp_f32_e32 v143, v143
	s_nop 0
	v_add_f32_e32 v143, 1.0, v143
	v_rcp_f32_e32 v149, v143
	v_and_b32_e32 v143, 0xffff0000, v146
	v_mul_f32_e32 v143, 0xbfb8aa3b, v143
	v_exp_f32_e32 v151, v143
	v_lshlrev_b32_e32 v143, 16, v145
	v_mul_f32_e32 v143, 0xbfb8aa3b, v143
	v_exp_f32_e32 v143, v143
	v_pk_add_f32 v[150:151], v[150:151], 1.0 op_sel_hi:[1,0]
	v_add_f32_e32 v143, 1.0, v143
	v_rcp_f32_e32 v144, v143
	v_lshlrev_b32_e32 v143, 16, v147
	v_mul_f32_e32 v143, 0xbfb8aa3b, v143
	v_exp_f32_e32 v146, v143
	v_and_b32_e32 v143, 0xffff0000, v145
	v_mul_f32_e32 v143, 0xbfb8aa3b, v143
	v_exp_f32_e32 v143, v143
	v_pk_mul_f32 v[148:149], v[148:149], v[150:151]
	v_add_f32_e32 v143, 1.0, v143
	v_rcp_f32_e32 v145, v143
	v_and_b32_e32 v143, 0xffff0000, v147
	v_mul_f32_e32 v143, 0xbfb8aa3b, v143
	v_exp_f32_e32 v147, v143
	s_nop 0
	v_lshlrev_b32_e32 v143, 16, v138
	v_and_b32_e32 v138, 0xffff0000, v138
	v_mul_f32_e32 v138, 0xbfb8aa3b, v138
	v_exp_f32_e32 v138, v138
	v_pk_add_f32 v[146:147], v[146:147], 1.0 op_sel_hi:[1,0]
	v_mul_f32_e32 v143, 0xbfb8aa3b, v143
	v_pk_mul_f32 v[144:145], v[144:145], v[146:147]
	v_add_f32_e32 v138, 1.0, v138
	v_pk_mul_f32 v[92:93], v[92:93], v[144:145]
	v_rcp_f32_e32 v145, v138
	s_nop 0
	v_and_b32_e32 v138, 0xffff0000, v140
	v_exp_f32_e32 v143, v143
	v_mul_f32_e32 v138, 0xbfb8aa3b, v138
	v_exp_f32_e32 v147, v138
	v_lshlrev_b32_e32 v138, 16, v139
	v_and_b32_e32 v139, 0xffff0000, v139
	v_mul_f32_e32 v138, 0xbfb8aa3b, v138
	v_mul_f32_e32 v139, 0xbfb8aa3b, v139
	v_exp_f32_e32 v138, v138
	v_exp_f32_e32 v139, v139
	v_add_f32_e32 v143, 1.0, v143
	v_rcp_f32_e32 v144, v143
	v_lshlrev_b32_e32 v143, 16, v140
	v_lshlrev_b32_e32 v140, 16, v141
	v_and_b32_e32 v141, 0xffff0000, v141
	v_mul_f32_e32 v140, 0xbfb8aa3b, v140
	v_mul_f32_e32 v141, 0xbfb8aa3b, v141
	v_add_f32_e32 v138, 1.0, v138
	v_exp_f32_e32 v140, v140
	v_add_f32_e32 v139, 1.0, v139
	v_exp_f32_e32 v141, v141
	v_rcp_f32_e32 v138, v138
	v_rcp_f32_e32 v139, v139
	v_mul_f32_e32 v143, 0xbfb8aa3b, v143
	v_exp_f32_e32 v146, v143
	v_pk_add_f32 v[140:141], v[140:141], 1.0 op_sel_hi:[1,0]
	v_pk_mul_f32 v[90:91], v[90:91], v[148:149]
	v_pk_mul_f32 v[138:139], v[138:139], v[140:141]
	v_pk_add_f32 v[146:147], v[146:147], 1.0 op_sel_hi:[1,0]
	v_pk_mul_f32 v[84:85], v[84:85], v[138:139]
	v_or_b32_e32 v138, 0x60, v142
	v_mad_i64_i32 v[140:141], s[26:27], v138, s35, v[136:137]
	v_pk_mul_f32 v[144:145], v[144:145], v[146:147]
	v_lshl_add_u64 v[138:139], v[140:141], 0, s[30:31]
	v_pk_mul_f32 v[82:83], v[82:83], v[144:145]
	v_lshl_add_u64 v[144:145], v[138:139], 0, v[0:1]
	s_waitcnt vmcnt(15)
	v_mov_b64_e32 v[144:145], v[198:199]
	v_lshl_add_u64 v[140:141], v[140:141], 0, s[42:43]
	v_lshl_add_u64 v[146:147], v[140:141], 0, v[0:1]
	s_waitcnt vmcnt(14)
	v_mov_b64_e32 v[146:147], v[200:201]
	s_nop 0
	v_lshlrev_b32_e32 v143, 16, v144
	v_mul_f32_e32 v143, 0xbfb8aa3b, v143
	v_exp_f32_e32 v143, v143
	s_nop 0
	v_add_f32_e32 v143, 1.0, v143
	v_rcp_f32_e32 v148, v143
	s_nop 0
	v_lshlrev_b32_e32 v143, 16, v146
	v_mul_f32_e32 v143, 0xbfb8aa3b, v143
	v_exp_f32_e32 v150, v143
	v_and_b32_e32 v143, 0xffff0000, v144
	v_mul_f32_e32 v143, 0xbfb8aa3b, v143
	v_exp_f32_e32 v143, v143
	s_nop 0
	v_add_f32_e32 v143, 1.0, v143
	v_rcp_f32_e32 v149, v143
	v_and_b32_e32 v143, 0xffff0000, v146
	v_mul_f32_e32 v143, 0xbfb8aa3b, v143
	v_exp_f32_e32 v151, v143
	v_lshlrev_b32_e32 v143, 16, v145
	v_mul_f32_e32 v143, 0xbfb8aa3b, v143
	v_exp_f32_e32 v143, v143
	v_pk_add_f32 v[150:151], v[150:151], 1.0 op_sel_hi:[1,0]
	v_add_f32_e32 v143, 1.0, v143
	v_rcp_f32_e32 v144, v143
	v_lshlrev_b32_e32 v143, 16, v147
	v_mul_f32_e32 v143, 0xbfb8aa3b, v143
	v_exp_f32_e32 v146, v143
	v_and_b32_e32 v143, 0xffff0000, v145
	v_mul_f32_e32 v143, 0xbfb8aa3b, v143
	v_exp_f32_e32 v143, v143
	v_pk_mul_f32 v[148:149], v[148:149], v[150:151]
	v_add_f32_e32 v143, 1.0, v143
	v_rcp_f32_e32 v145, v143
	v_and_b32_e32 v143, 0xffff0000, v147
	v_mul_f32_e32 v143, 0xbfb8aa3b, v143
	v_exp_f32_e32 v147, v143
	v_pk_mul_f32 v[74:75], v[74:75], v[148:149]
	v_pk_add_f32 v[146:147], v[146:147], 1.0 op_sel_hi:[1,0]
	s_nop 0
	v_pk_mul_f32 v[144:145], v[144:145], v[146:147]
	v_lshl_add_u64 v[146:147], v[140:141], 0, v[134:135]
	v_pk_mul_f32 v[76:77], v[76:77], v[144:145]
	v_lshl_add_u64 v[144:145], v[138:139], 0, v[134:135]
	s_waitcnt vmcnt(13)
	v_mov_b64_e32 v[144:145], v[202:203]
	s_nop 0
	s_waitcnt vmcnt(12)
	v_mov_b64_e32 v[146:147], v[204:205]
	s_nop 0
	v_lshlrev_b32_e32 v143, 16, v144
	v_mul_f32_e32 v143, 0xbfb8aa3b, v143
	v_exp_f32_e32 v143, v143
	s_nop 0
	v_add_f32_e32 v143, 1.0, v143
	v_rcp_f32_e32 v148, v143
	s_nop 0
	v_lshlrev_b32_e32 v143, 16, v146
	v_mul_f32_e32 v143, 0xbfb8aa3b, v143
	v_exp_f32_e32 v150, v143
	v_and_b32_e32 v143, 0xffff0000, v144
	v_mul_f32_e32 v143, 0xbfb8aa3b, v143
	v_exp_f32_e32 v143, v143
	s_nop 0
	v_add_f32_e32 v143, 1.0, v143
	v_rcp_f32_e32 v149, v143
	v_and_b32_e32 v143, 0xffff0000, v146
	v_mul_f32_e32 v143, 0xbfb8aa3b, v143
	v_exp_f32_e32 v151, v143
	v_lshlrev_b32_e32 v143, 16, v145
	v_mul_f32_e32 v143, 0xbfb8aa3b, v143
	v_exp_f32_e32 v143, v143
	v_pk_add_f32 v[150:151], v[150:151], 1.0 op_sel_hi:[1,0]
	v_add_f32_e32 v143, 1.0, v143
	v_rcp_f32_e32 v144, v143
	v_lshlrev_b32_e32 v143, 16, v147
	v_mul_f32_e32 v143, 0xbfb8aa3b, v143
	v_exp_f32_e32 v146, v143
	v_and_b32_e32 v143, 0xffff0000, v145
	v_mul_f32_e32 v143, 0xbfb8aa3b, v143
	v_exp_f32_e32 v143, v143
	v_pk_mul_f32 v[148:149], v[148:149], v[150:151]
	v_add_f32_e32 v143, 1.0, v143
	v_rcp_f32_e32 v145, v143
	v_and_b32_e32 v143, 0xffff0000, v147
	v_mul_f32_e32 v143, 0xbfb8aa3b, v143
	v_exp_f32_e32 v147, v143
	v_pk_mul_f32 v[66:67], v[66:67], v[148:149]
	v_pk_add_f32 v[146:147], v[146:147], 1.0 op_sel_hi:[1,0]
	s_nop 0
	v_pk_mul_f32 v[144:145], v[144:145], v[146:147]
	v_lshl_add_u64 v[146:147], v[140:141], 0, v[132:133]
	v_pk_mul_f32 v[68:69], v[68:69], v[144:145]
	v_lshl_add_u64 v[144:145], v[138:139], 0, v[132:133]
	s_waitcnt vmcnt(11)
; DI float bflo(unsigned u) { return __uint_as_float(u << 16); }
; DI float bfhi(unsigned u) { return __uint_as_float(u & 0xffff0000u); }
; DI float sigmoidf(float x) { return __builtin_amdgcn_rcpf(1.f + __expf(-x)); }
; DI float inv_sigmoidf(float x) { return 1.f + __expf(-x); }
; DI int TID8() { int t = threadIdx.x; asm volatile("" : "+v"(t)); return t; }
; template <class E>
; DI void gemm8_epi(f32x4 (&acc)[8][4], int m0, int n0, E e) {
;   const int tid = TID8(), lane = tid & 63, w = tid >> 6;
;   const int wm = w >> 2, wn = w & 3;
; #pragma unroll
;   for (int i = 0; i < 8; ++i)
; #pragma unroll
;     for (int j = 0; j < 4; ++j) {
;       const int m = m0 + wm * 128 + i * 16 + (lane & 15);
;       const int n = n0 + wn * 64 + j * 16 + (lane >> 4) * 4;
;       e(m, n, acc[i][j]);
;     }
; }
; __global__ void __launch_bounds__(512, 2) mega(Params p) {
;     ...
;       gemm8_epi(acc8, m0, n0, [&](int m, int n, f32x4& a) {
;         uint2 ua = *(const uint2*)(z + (size_t)m * ZS + C_MA + n);
;         uint2 ub = *(const uint2*)(z + (size_t)m * ZS + C_MB + n);
;         a[0] *= sigmoidf(bflo(ua.x)) * inv_sigmoidf(bflo(ub.x));
;         a[1] *= sigmoidf(bfhi(ua.x)) * inv_sigmoidf(bfhi(ub.x));
;         a[2] *= sigmoidf(bflo(ua.y)) * inv_sigmoidf(bflo(ub.y));
;         a[3] *= sigmoidf(bfhi(ua.y)) * inv_sigmoidf(bfhi(ub.y));
;       });
	v_mov_b64_e32 v[144:145], v[206:207]
	v_lshl_add_u64 v[138:139], v[138:139], 0, v[130:131]
	s_waitcnt vmcnt(10)
	v_mov_b64_e32 v[146:147], v[208:209]
	v_lshl_add_u64 v[140:141], v[140:141], 0, v[130:131]
	s_waitcnt vmcnt(9)
	v_mov_b64_e32 v[138:139], v[210:211]
	s_nop 0
	s_waitcnt vmcnt(8)
	v_mov_b64_e32 v[140:141], v[212:213]
	s_nop 0
	v_lshlrev_b32_e32 v143, 16, v144
	v_mul_f32_e32 v143, 0xbfb8aa3b, v143
	v_exp_f32_e32 v143, v143
	s_nop 0
	v_add_f32_e32 v143, 1.0, v143
	v_rcp_f32_e32 v148, v143
	s_nop 0
	v_lshlrev_b32_e32 v143, 16, v146
	v_mul_f32_e32 v143, 0xbfb8aa3b, v143
	v_exp_f32_e32 v150, v143
	v_and_b32_e32 v143, 0xffff0000, v144
	v_mul_f32_e32 v143, 0xbfb8aa3b, v143
	v_exp_f32_e32 v143, v143
	s_nop 0
	v_add_f32_e32 v143, 1.0, v143
	v_rcp_f32_e32 v149, v143
	v_and_b32_e32 v143, 0xffff0000, v146
	v_mul_f32_e32 v143, 0xbfb8aa3b, v143
	v_exp_f32_e32 v151, v143
	v_lshlrev_b32_e32 v143, 16, v145
	v_mul_f32_e32 v143, 0xbfb8aa3b, v143
	v_exp_f32_e32 v143, v143
	v_pk_add_f32 v[150:151], v[150:151], 1.0 op_sel_hi:[1,0]
	v_add_f32_e32 v143, 1.0, v143
	v_rcp_f32_e32 v144, v143
	v_lshlrev_b32_e32 v143, 16, v147
	v_mul_f32_e32 v143, 0xbfb8aa3b, v143
	v_exp_f32_e32 v146, v143
	v_and_b32_e32 v143, 0xffff0000, v145
	v_mul_f32_e32 v143, 0xbfb8aa3b, v143
	v_exp_f32_e32 v143, v143
	v_pk_mul_f32 v[148:149], v[148:149], v[150:151]
	v_add_f32_e32 v143, 1.0, v143
	v_rcp_f32_e32 v145, v143
	v_and_b32_e32 v143, 0xffff0000, v147
	v_mul_f32_e32 v143, 0xbfb8aa3b, v143
	v_exp_f32_e32 v147, v143
	s_nop 0
	v_lshlrev_b32_e32 v143, 16, v138
	v_and_b32_e32 v138, 0xffff0000, v138
	v_mul_f32_e32 v138, 0xbfb8aa3b, v138
	v_exp_f32_e32 v138, v138
	v_pk_add_f32 v[146:147], v[146:147], 1.0 op_sel_hi:[1,0]
	v_mul_f32_e32 v143, 0xbfb8aa3b, v143
	v_pk_mul_f32 v[144:145], v[144:145], v[146:147]
	v_add_f32_e32 v138, 1.0, v138
	v_pk_mul_f32 v[60:61], v[60:61], v[144:145]
	v_rcp_f32_e32 v145, v138
	s_nop 0
	v_and_b32_e32 v138, 0xffff0000, v140
	v_exp_f32_e32 v143, v143
	v_mul_f32_e32 v138, 0xbfb8aa3b, v138
	v_exp_f32_e32 v147, v138
	v_lshlrev_b32_e32 v138, 16, v139
	v_and_b32_e32 v139, 0xffff0000, v139
	v_mul_f32_e32 v138, 0xbfb8aa3b, v138
	v_mul_f32_e32 v139, 0xbfb8aa3b, v139
	v_exp_f32_e32 v138, v138
	v_exp_f32_e32 v139, v139
	v_add_f32_e32 v143, 1.0, v143
	v_rcp_f32_e32 v144, v143
	v_lshlrev_b32_e32 v143, 16, v140
	v_lshlrev_b32_e32 v140, 16, v141
	v_and_b32_e32 v141, 0xffff0000, v141
	v_mul_f32_e32 v140, 0xbfb8aa3b, v140
	v_mul_f32_e32 v141, 0xbfb8aa3b, v141
	v_add_f32_e32 v138, 1.0, v138
	v_exp_f32_e32 v140, v140
	v_add_f32_e32 v139, 1.0, v139
	v_exp_f32_e32 v141, v141
	v_rcp_f32_e32 v138, v138
	v_rcp_f32_e32 v139, v139
	v_mul_f32_e32 v143, 0xbfb8aa3b, v143
	v_pk_add_f32 v[140:141], v[140:141], 1.0 op_sel_hi:[1,0]
	v_exp_f32_e32 v146, v143
	v_pk_mul_f32 v[138:139], v[138:139], v[140:141]
	v_pk_mul_f32 v[58:59], v[58:59], v[148:149]
	v_pk_mul_f32 v[52:53], v[52:53], v[138:139]
	v_or_b32_e32 v138, 0x70, v142
	v_mad_i64_i32 v[138:139], s[26:27], v138, s35, v[136:137]
	v_lshl_add_u64 v[136:137], v[138:139], 0, s[30:31]
	v_lshl_add_u64 v[140:141], v[136:137], 0, v[0:1]
	s_waitcnt vmcnt(7)
	v_mov_b64_e32 v[140:141], v[214:215]
	v_lshl_add_u64 v[138:139], v[138:139], 0, s[42:43]
	v_lshl_add_u64 v[142:143], v[138:139], 0, v[0:1]
	s_waitcnt vmcnt(6)
	v_mov_b64_e32 v[142:143], v[216:217]
	v_pk_add_f32 v[146:147], v[146:147], 1.0 op_sel_hi:[1,0]
	s_nop 0
	v_lshlrev_b32_e32 v0, 16, v140
	v_mul_f32_e32 v0, 0xbfb8aa3b, v0
	v_exp_f32_e32 v0, v0
	v_pk_mul_f32 v[144:145], v[144:145], v[146:147]
	v_add_f32_e32 v0, 1.0, v0
	v_pk_mul_f32 v[50:51], v[50:51], v[144:145]
	v_rcp_f32_e32 v144, v0
	s_nop 0
	v_lshlrev_b32_e32 v0, 16, v142
	v_mul_f32_e32 v0, 0xbfb8aa3b, v0
	v_exp_f32_e32 v146, v0
	v_and_b32_e32 v0, 0xffff0000, v140
	v_mul_f32_e32 v0, 0xbfb8aa3b, v0
	v_exp_f32_e32 v0, v0
	s_nop 0
	v_add_f32_e32 v0, 1.0, v0
	v_rcp_f32_e32 v145, v0
	v_and_b32_e32 v0, 0xffff0000, v142
	v_mul_f32_e32 v0, 0xbfb8aa3b, v0
	v_exp_f32_e32 v147, v0
	v_lshlrev_b32_e32 v0, 16, v141
	v_mul_f32_e32 v0, 0xbfb8aa3b, v0
	v_exp_f32_e32 v0, v0
	v_pk_add_f32 v[146:147], v[146:147], 1.0 op_sel_hi:[1,0]
	v_add_f32_e32 v0, 1.0, v0
	v_rcp_f32_e32 v140, v0
	v_lshlrev_b32_e32 v0, 16, v143
	v_mul_f32_e32 v0, 0xbfb8aa3b, v0
	v_exp_f32_e32 v142, v0
	v_and_b32_e32 v0, 0xffff0000, v141
	v_mul_f32_e32 v0, 0xbfb8aa3b, v0
	v_exp_f32_e32 v0, v0
	v_pk_mul_f32 v[144:145], v[144:145], v[146:147]
	v_add_f32_e32 v0, 1.0, v0
	v_rcp_f32_e32 v141, v0
	v_and_b32_e32 v0, 0xffff0000, v143
	v_mul_f32_e32 v0, 0xbfb8aa3b, v0
	v_exp_f32_e32 v143, v0
	v_pk_mul_f32 v[42:43], v[42:43], v[144:145]
	v_pk_add_f32 v[142:143], v[142:143], 1.0 op_sel_hi:[1,0]
	s_nop 0
	v_pk_mul_f32 v[140:141], v[140:141], v[142:143]
	s_nop 0
	v_pk_mul_f32 v[44:45], v[44:45], v[140:141]
	v_lshl_add_u64 v[140:141], v[136:137], 0, v[134:135]
	s_waitcnt vmcnt(5)
	v_mov_b64_e32 v[140:141], v[218:219]
	v_lshl_add_u64 v[134:135], v[138:139], 0, v[134:135]
	s_waitcnt vmcnt(4)
; DI float bflo(unsigned u) { return __uint_as_float(u << 16); }
; DI float bfhi(unsigned u) { return __uint_as_float(u & 0xffff0000u); }
; DI float sigmoidf(float x) { return __builtin_amdgcn_rcpf(1.f + __expf(-x)); }
; DI float inv_sigmoidf(float x) { return 1.f + __expf(-x); }
; DI int TID8() { int t = threadIdx.x; asm volatile("" : "+v"(t)); return t; }
; template <class E>
; DI void gemm8_epi(f32x4 (&acc)[8][4], int m0, int n0, E e) {
;   const int tid = TID8(), lane = tid & 63, w = tid >> 6;
;   const int wm = w >> 2, wn = w & 3;
; #pragma unroll
;   for (int i = 0; i < 8; ++i)
; #pragma unroll
;     for (int j = 0; j < 4; ++j) {
;       const int m = m0 + wm * 128 + i * 16 + (lane & 15);
;       const int n = n0 + wn * 64 + j * 16 + (lane >> 4) * 4;
;       e(m, n, acc[i][j]);
;     }
; }
; __global__ void __launch_bounds__(512, 2) mega(Params p) {
;     ...
;       gemm8_epi(acc8, m0, n0, [&](int m, int n, f32x4& a) {
;         uint2 ua = *(const uint2*)(z + (size_t)m * ZS + C_MA + n);
;         uint2 ub = *(const uint2*)(z + (size_t)m * ZS + C_MB + n);
;         a[0] *= sigmoidf(bflo(ua.x)) * inv_sigmoidf(bflo(ub.x));
;         a[1] *= sigmoidf(bfhi(ua.x)) * inv_sigmoidf(bfhi(ub.x));
;         a[2] *= sigmoidf(bflo(ua.y)) * inv_sigmoidf(bflo(ub.y));
;         a[3] *= sigmoidf(bfhi(ua.y)) * inv_sigmoidf(bfhi(ub.y));
;       });
	v_mov_b64_e32 v[134:135], v[220:221]
	s_nop 0
	v_lshlrev_b32_e32 v0, 16, v140
	v_mul_f32_e32 v0, 0xbfb8aa3b, v0
	v_exp_f32_e32 v0, v0
	s_nop 0
	v_add_f32_e32 v0, 1.0, v0
	v_rcp_f32_e32 v142, v0
	s_nop 0
	v_lshlrev_b32_e32 v0, 16, v134
	v_mul_f32_e32 v0, 0xbfb8aa3b, v0
	v_exp_f32_e32 v144, v0
	v_and_b32_e32 v0, 0xffff0000, v140
	v_mul_f32_e32 v0, 0xbfb8aa3b, v0
	v_exp_f32_e32 v0, v0
	s_nop 0
	v_add_f32_e32 v0, 1.0, v0
	v_rcp_f32_e32 v143, v0
	v_and_b32_e32 v0, 0xffff0000, v134
	v_mul_f32_e32 v0, 0xbfb8aa3b, v0
	v_exp_f32_e32 v145, v0
	v_lshlrev_b32_e32 v0, 16, v141
	v_mul_f32_e32 v0, 0xbfb8aa3b, v0
	v_exp_f32_e32 v0, v0
	v_pk_add_f32 v[144:145], v[144:145], 1.0 op_sel_hi:[1,0]
	v_add_f32_e32 v0, 1.0, v0
	v_rcp_f32_e32 v140, v0
	v_lshlrev_b32_e32 v0, 16, v135
	v_mul_f32_e32 v0, 0xbfb8aa3b, v0
	v_exp_f32_e32 v134, v0
	v_and_b32_e32 v0, 0xffff0000, v141
	v_mul_f32_e32 v0, 0xbfb8aa3b, v0
	v_exp_f32_e32 v0, v0
	v_pk_mul_f32 v[142:143], v[142:143], v[144:145]
	v_mov_b32_e32 v145, v1
	v_pk_mul_f32 v[34:35], v[34:35], v[142:143]
	v_add_f32_e32 v0, 1.0, v0
	v_rcp_f32_e32 v141, v0
	v_and_b32_e32 v0, 0xffff0000, v135
	v_mul_f32_e32 v0, 0xbfb8aa3b, v0
	v_exp_f32_e32 v135, v0
	s_nop 0
	v_pk_add_f32 v[134:135], v[134:135], 1.0 op_sel_hi:[1,0]
	s_nop 0
	v_pk_mul_f32 v[134:135], v[140:141], v[134:135]
	s_nop 0
	v_pk_mul_f32 v[36:37], v[36:37], v[134:135]
	v_lshl_add_u64 v[134:135], v[136:137], 0, v[132:133]
	s_waitcnt vmcnt(3)
	v_mov_b64_e32 v[134:135], v[222:223]
	v_lshl_add_u64 v[132:133], v[138:139], 0, v[132:133]
	s_waitcnt vmcnt(2)
	v_mov_b64_e32 v[132:133], v[224:225]
	s_nop 0
	v_lshlrev_b32_e32 v0, 16, v134
	v_mul_f32_e32 v0, 0xbfb8aa3b, v0
	v_exp_f32_e32 v0, v0
	s_nop 0
	v_add_f32_e32 v0, 1.0, v0
	v_rcp_f32_e32 v140, v0
	s_nop 0
	v_lshlrev_b32_e32 v0, 16, v132
	v_mul_f32_e32 v0, 0xbfb8aa3b, v0
	v_exp_f32_e32 v142, v0
	v_and_b32_e32 v0, 0xffff0000, v134
	v_mul_f32_e32 v0, 0xbfb8aa3b, v0
	v_exp_f32_e32 v0, v0
	s_nop 0
	v_add_f32_e32 v0, 1.0, v0
	v_rcp_f32_e32 v141, v0
	v_and_b32_e32 v0, 0xffff0000, v132
	v_mul_f32_e32 v0, 0xbfb8aa3b, v0
	v_exp_f32_e32 v143, v0
	v_lshlrev_b32_e32 v0, 16, v135
	v_mul_f32_e32 v0, 0xbfb8aa3b, v0
	v_exp_f32_e32 v0, v0
	v_pk_add_f32 v[142:143], v[142:143], 1.0 op_sel_hi:[1,0]
	v_add_f32_e32 v0, 1.0, v0
	v_rcp_f32_e32 v134, v0
	v_lshlrev_b32_e32 v0, 16, v133
	v_mul_f32_e32 v0, 0xbfb8aa3b, v0
	v_exp_f32_e32 v132, v0
	v_and_b32_e32 v0, 0xffff0000, v135
	v_mul_f32_e32 v0, 0xbfb8aa3b, v0
	v_exp_f32_e32 v0, v0
	v_pk_mul_f32 v[140:141], v[140:141], v[142:143]
	v_mov_b32_e32 v143, v1
	v_pk_mul_f32 v[26:27], v[26:27], v[140:141]
	v_add_f32_e32 v0, 1.0, v0
	v_rcp_f32_e32 v135, v0
	v_and_b32_e32 v0, 0xffff0000, v133
	v_mul_f32_e32 v0, 0xbfb8aa3b, v0
	v_exp_f32_e32 v133, v0
	s_nop 0
	v_pk_add_f32 v[132:133], v[132:133], 1.0 op_sel_hi:[1,0]
	s_nop 0
	v_pk_mul_f32 v[132:133], v[134:135], v[132:133]
	s_nop 0
	v_pk_mul_f32 v[28:29], v[28:29], v[132:133]
	v_lshl_add_u64 v[132:133], v[136:137], 0, v[130:131]
	s_waitcnt vmcnt(1)
	v_mov_b64_e32 v[132:133], v[226:227]
	v_lshl_add_u64 v[130:131], v[138:139], 0, v[130:131]
	s_waitcnt vmcnt(0)
; DI float bflo(unsigned u) { return __uint_as_float(u << 16); }
; DI float bfhi(unsigned u) { return __uint_as_float(u & 0xffff0000u); }
; DI float sigmoidf(float x) { return __builtin_amdgcn_rcpf(1.f + __expf(-x)); }
; DI float inv_sigmoidf(float x) { return 1.f + __expf(-x); }
; DI int TID8() { int t = threadIdx.x; asm volatile("" : "+v"(t)); return t; }
; DI void gemm8_accum(f32x4 (&acc)[8][4], const bf16_t* a, size_t lda, const bf16_t* b, size_t ldb, int nkb, bf16_t* L,
;                     const bool pre, const bf16_t* an, size_t ldan, const bf16_t* bn, size_t ldbn) {
;   const int tid = TID8(), lane = tid & 63, w = tid >> 6;
;   const int wm = w >> 2, wn = w & 3;
;   const int lrow = tid >> 3, lch = tid & 7;
;   u32x4 ra[4], rb[4];
;   unsigned offa[4], offb[4];
; #pragma unroll
;   for (int i = 0; i < 4; ++i) {
;     offa[i] = (unsigned)(lrow + 64 * i) * (unsigned)lda + (unsigned)(lch * 8);
;     offb[i] = (unsigned)(lrow + 64 * i) * (unsigned)ldb + (unsigned)(lch * 8);
;   }
;   if (!pre) {
;     g8_load1o(ra, a, offa);
;     g8_load1o(rb, b, offb);
;     __syncthreads();
;     g8_store(L, ra, rb, lrow, lch);
;   }
;   g8_load1o(ra, a + 64, offa);
;   g8_load1o(rb, b + 64, offb);
; __global__ void __launch_bounds__(512, 2) mega(Params p) {
;     ...
;       gemm8_epi(acc8, m0, n0, [&](int m, int n, f32x4& a) {
;         uint2 ua = *(const uint2*)(z + (size_t)m * ZS + C_MA + n);
;         uint2 ub = *(const uint2*)(z + (size_t)m * ZS + C_MB + n);
;         a[0] *= sigmoidf(bflo(ua.x)) * inv_sigmoidf(bflo(ub.x));
;         a[1] *= sigmoidf(bfhi(ua.x)) * inv_sigmoidf(bfhi(ub.x));
;         a[2] *= sigmoidf(bflo(ua.y)) * inv_sigmoidf(bflo(ub.y));
;         a[3] *= sigmoidf(bfhi(ua.y)) * inv_sigmoidf(bfhi(ub.y));
;       });
	v_mov_b64_e32 v[130:131], v[228:229]
	v_mov_b32_e32 v139, v1
	v_ashrrev_i32_e32 v173, 3, v172
	v_lshrrev_b32_e32 v140, 1, v173
	v_xor_b32_e32 v140, v140, v172
	v_lshlrev_b32_e32 v140, 3, v140
	v_and_b32_e32 v174, 56, v140
	v_lshrrev_b32_e32 v175, 1, v172
	v_bfe_u32 v176, v172, 1, 3
	v_lshlrev_b32_e32 v191, 1, v174
	v_lshlrev_b32_e32 v163, 6, v173
	s_nop 0
	v_lshlrev_b32_e32 v0, 16, v132
	v_mul_f32_e32 v0, 0xbfb8aa3b, v0
	v_exp_f32_e32 v0, v0
	s_nop 0
	v_add_f32_e32 v0, 1.0, v0
	v_rcp_f32_e32 v134, v0
	s_nop 0
	v_lshlrev_b32_e32 v0, 16, v130
	v_mul_f32_e32 v0, 0xbfb8aa3b, v0
	v_exp_f32_e32 v136, v0
	v_and_b32_e32 v0, 0xffff0000, v132
	v_mul_f32_e32 v0, 0xbfb8aa3b, v0
	v_exp_f32_e32 v0, v0
	s_nop 0
	v_add_f32_e32 v0, 1.0, v0
	v_rcp_f32_e32 v135, v0
	v_and_b32_e32 v0, 0xffff0000, v130
	v_mul_f32_e32 v0, 0xbfb8aa3b, v0
	v_exp_f32_e32 v137, v0
	v_lshlrev_b32_e32 v0, 16, v133
	v_mul_f32_e32 v0, 0xbfb8aa3b, v0
	v_exp_f32_e32 v0, v0
	v_pk_add_f32 v[136:137], v[136:137], 1.0 op_sel_hi:[1,0]
	v_add_f32_e32 v0, 1.0, v0
	v_rcp_f32_e32 v132, v0
	v_lshlrev_b32_e32 v0, 16, v131
	v_mul_f32_e32 v0, 0xbfb8aa3b, v0
	v_exp_f32_e32 v130, v0
	v_and_b32_e32 v0, 0xffff0000, v133
	v_mul_f32_e32 v0, 0xbfb8aa3b, v0
	v_exp_f32_e32 v0, v0
	v_pk_mul_f32 v[134:135], v[134:135], v[136:137]
	v_mov_b32_e32 v137, v1
	v_pk_mul_f32 v[18:19], v[18:19], v[134:135]
	v_add_f32_e32 v0, 1.0, v0
	v_rcp_f32_e32 v133, v0
	v_and_b32_e32 v0, 0xffff0000, v131
	v_mul_f32_e32 v0, 0xbfb8aa3b, v0
	v_exp_f32_e32 v131, v0
	v_lshlrev_b32_e32 v0, 3, v172
	v_and_b32_e32 v0, 56, v0
	v_mov_b32_e32 v135, v1
	v_pk_add_f32 v[130:131], v[130:131], 1.0 op_sel_hi:[1,0]
	s_nop 0
	v_pk_mul_f32 v[130:131], v[132:133], v[130:131]
	v_lshl_or_b32 v132, v173, 9, v0
	v_pk_mul_f32 v[20:21], v[20:21], v[130:131]
	v_mad_u64_u32 v[130:131], s[26:27], v173, s25, v[0:1]
	v_mov_b32_e32 v131, v1
	v_add_u32_e32 v144, 0x18000, v132
	v_add_u32_e32 v0, 0x54600, v130
	v_add_u32_e32 v142, 0x10000, v132
	v_lshlrev_b64 v[186:187], 1, v[130:131]
	v_lshlrev_b64 v[170:171], 1, v[144:145]
	v_add_u32_e32 v136, 0xa8c00, v130
	v_add_u32_e32 v138, 0xfd200, v130
	v_lshl_add_u64 v[130:131], s[2:3], 0, v[186:187]
	v_lshlrev_b64 v[184:185], 1, v[0:1]
	v_lshlrev_b64 v[168:169], 1, v[142:143]
	v_lshl_add_u64 v[142:143], s[6:7], 0, v[170:171]
	global_load_dwordx4 v[146:149], v[130:131], off offset:2736
	v_lshlrev_b64 v[182:183], 1, v[136:137]
	global_load_dwordx4 v[142:145], v[142:143], off offset:128
	v_lshl_add_u64 v[130:131], s[2:3], 0, v[184:185]
	v_add_u32_e32 v134, 0x8000, v132
	v_mov_b32_e32 v133, v1
	global_load_dwordx4 v[150:153], v[130:131], off offset:2736
	v_lshl_add_u64 v[130:131], s[2:3], 0, v[182:183]
	v_lshlrev_b64 v[180:181], 1, v[138:139]
	global_load_dwordx4 v[154:157], v[130:131], off offset:2736
	v_lshl_add_u64 v[130:131], s[2:3], 0, v[180:181]
	v_lshlrev_b64 v[164:165], 1, v[132:133]
	v_lshlrev_b64 v[166:167], 1, v[134:135]
	global_load_dwordx4 v[158:161], v[130:131], off offset:2736
	v_lshl_add_u64 v[130:131], s[6:7], 0, v[164:165]
	v_lshl_add_u64 v[134:135], s[6:7], 0, v[166:167]
	global_load_dwordx4 v[130:133], v[130:131], off offset:128
	v_bfe_u32 v0, v172, 4, 2
	global_load_dwordx4 v[138:141], v[134:135], off offset:128
	v_lshl_add_u64 v[134:135], s[6:7], 0, v[168:169]
	global_load_dwordx4 v[134:137], v[134:135], off offset:128
	v_bitop3_b32 v175, v175, v0, 7 bitop3:0x6c
	v_lshlrev_b32_e32 v192, 3, v175
	v_lshlrev_b32_e32 v175, 5, v172
	v_and_b32_e32 v175, 0xffffe000, v175
	v_lshlrev_b32_e32 v172, 6, v172
	v_and_or_b32 v188, v172, s1, v175
	v_readlane_b32 s1, v254, 20
	s_add_u32 s2, s1, s21
	v_readlane_b32 s1, v254, 21
	s_addc_u32 s3, s1, 0
	v_readlane_b32 s1, v254, 22
	v_bitop3_b32 v0, v0, v176, 4 bitop3:0x36
	s_add_u32 s0, s1, s0
	v_readlane_b32 s1, v254, 23
	v_and_b32_e32 v193, 0x33c0, v172
	v_lshlrev_b32_e32 v190, 3, v0
	v_lshlrev_b32_e32 v0, 7, v173
	s_addc_u32 s1, s1, 0
	v_add3_u32 v0, 0, v191, v0
	v_lshl_add_u64 v[172:173], s[2:3], 0, v[170:171]
	v_lshl_add_u64 v[174:175], s[2:3], 0, v[168:169]
	v_lshl_add_u64 v[176:177], s[2:3], 0, v[166:167]
	v_lshl_add_u64 v[178:179], s[2:3], 0, v[164:165]
	v_lshl_add_u64 v[180:181], s[0:1], 0, v[180:181]
	v_lshl_add_u64 v[182:183], s[0:1], 0, v[182:183]
	v_lshl_add_u64 v[184:185], s[0:1], 0, v[184:185]
	v_lshl_add_u64 v[186:187], s[0:1], 0, v[186:187]
	s_mov_b64 s[0:1], 0
	s_mov_b32 s2, 0
	v_lshlrev_b32_e32 v189, 1, v188
	v_lshlrev_b32_e32 v188, 1, v193
